# P0 fast path + nt (non-temporal) loads for read-once x and w_in streams
# speedup vs baseline: 1.0328x; 1.0328x over previous
; __device__ __forceinline__ unsigned cvt_pk_bf16(float lo, float hi) { unsigned r; asm volatile("v_cvt_pk_bf16_f32 %0, %1, %2" : "=v"(r) : "v"(lo), "v"(hi)); return r; }
; __global__ void __launch_bounds__(512, 2) hybrid_fwd(Args a) {
;     ...
;         const size_t gt = (size_t)bx * 512 + tid, GT = (size_t)G * 512;
;         {
;             const size_t NCH = (size_t)M * D / 8;
;             for (size_t i0 = gt; i0 < NCH; i0 += 4 * GT) {
;                 f32x4 v[4][2];
; #pragma unroll
;                 for (int u = 0; u < 4; ++u) { const size_t i = i0 + (size_t)u * GT; if (i < NCH) { v[u][0] = ((const f32x4*)a.x)[2 * i]; v[u][1] = ((const f32x4*)a.x)[2 * i + 1]; } }
; #pragma unroll
;                 for (int u = 0; u < 4; ++u) { const size_t i = i0 + (size_t)u * GT; if (i < NCH) {
;                     u32x4 w; w.x = cvt_pk_bf16(v[u][0][0], v[u][0][1]); w.y = cvt_pk_bf16(v[u][0][2], v[u][0][3]); w.z = cvt_pk_bf16(v[u][1][0], v[u][1][1]); w.w = cvt_pk_bf16(v[u][1][2], v[u][1][3]);
;                     if (a.n_bf16 > 0) ((u32x4*)XB)[i] = w;
;                     const unsigned p0 = pack_fp8x4(v[u][0][0], v[u][0][1], v[u][0][2], v[u][0][3]), p1 = pack_fp8x4(v[u][1][0], v[u][1][1], v[u][1][2], v[u][1][3]);
;                     ((u32x2*)XB8)[i] = (u32x2){p0, p1}; } }
.LBB0_2:
	s_or_b64 exec, exec, s[4:5]
	s_ashr_i32 s3, s2, 31
	s_lshl_b64 s[4:5], s[2:3], 9
	v_mov_b32_e32 v161, 0
	v_lshl_add_u64 v[38:39], s[4:5], 0, v[160:161]
	s_waitcnt lgkmcnt(0)
	s_ashr_i32 s93, s92, 31
	s_mov_b64 s[12:13], 0x400000
	s_lshl_b64 s[14:15], s[92:93], 9
	v_cmp_gt_u64_e32 vcc, s[12:13], v[38:39]
	v_lshlrev_b32_e32 v40, 3, v160
	s_mov_b32 s100, 0
	s_cmp_lg_u32 s92, 0x100
	s_cbranch_scc1 .Lp0_done
	s_load_dword s16, s[70:71], 0x1c0
	s_load_dwordx2 s[18:19], s[70:71], 0x1c8
	s_load_dwordx2 s[6:7], s[70:71], 0x0
	s_load_dwordx2 s[20:21], s[70:71], 0x8
	s_load_dwordx2 s[22:23], s[70:71], 0x10
	s_waitcnt lgkmcnt(0)
	s_cmp_lg_u32 s16, 0
	s_cbranch_scc1 .Lp0_done
	s_cmp_lg_u32 s18, -1
	s_cbranch_scc1 .Lp0_done
	s_cmpk_lg_u32 s19, 0x1fff
	s_cbranch_scc1 .Lp0_done
	v_lshl_add_u32 v1, s2, 9, v160
	v_and_b32_e32 v4, 63, v160
	v_lshlrev_b32_e32 v2, 5, v1
	v_lshlrev_b32_e32 v3, 3, v1
	s_mov_b64 s[8:9], s[88:89]
	global_load_dwordx4 v[64:67], v2, s[6:7] nt
	global_load_dwordx4 v[68:71], v2, s[6:7] offset:16 nt
	s_add_u32 s6, s6, 0x400000
	s_addc_u32 s7, s7, 0
	global_load_dwordx4 v[72:75], v2, s[6:7] nt
	global_load_dwordx4 v[76:79], v2, s[6:7] offset:16 nt
	s_add_u32 s6, s6, 0x400000
	s_addc_u32 s7, s7, 0
	global_load_dwordx4 v[80:83], v2, s[6:7] nt
	global_load_dwordx4 v[84:87], v2, s[6:7] offset:16 nt
	s_add_u32 s6, s6, 0x400000
	s_addc_u32 s7, s7, 0
	global_load_dwordx4 v[88:91], v2, s[6:7] nt
	global_load_dwordx4 v[92:95], v2, s[6:7] offset:16 nt
	s_add_u32 s6, s6, 0x400000
	s_addc_u32 s7, s7, 0
	global_load_dwordx4 v[96:99], v2, s[6:7] nt
	global_load_dwordx4 v[100:103], v2, s[6:7] offset:16 nt
	s_add_u32 s6, s6, 0x400000
	s_addc_u32 s7, s7, 0
	global_load_dwordx4 v[104:107], v2, s[6:7] nt
	global_load_dwordx4 v[108:111], v2, s[6:7] offset:16 nt
	s_add_u32 s6, s6, 0x400000
	s_addc_u32 s7, s7, 0
	global_load_dwordx4 v[112:115], v2, s[6:7] nt
	global_load_dwordx4 v[116:119], v2, s[6:7] offset:16 nt
	s_add_u32 s6, s6, 0x400000
	s_addc_u32 s7, s7, 0
	global_load_dwordx4 v[120:123], v2, s[6:7] nt
	global_load_dwordx4 v[124:127], v2, s[6:7] offset:16 nt
	s_add_u32 s6, s6, 0x400000
	s_addc_u32 s7, s7, 0
	s_waitcnt vmcnt(14)
	v_cvt_pk_fp8_f32 v8, v64, v65
	v_cvt_pk_fp8_f32 v9, v66, v67
	v_cvt_pk_fp8_f32 v10, v68, v69
	v_cvt_pk_fp8_f32 v11, v70, v71
	v_and_b32_e32 v8, 0xffff, v8
	v_and_b32_e32 v10, 0xffff, v10
	v_lshl_or_b32 v128, v9, 16, v8
	v_lshl_or_b32 v129, v11, 16, v10
	global_store_dwordx2 v3, v[128:129], s[8:9]
	s_add_u32 s8, s8, 0x100000
	s_addc_u32 s9, s9, 0
	global_load_dwordx4 v[64:67], v2, s[6:7] nt
	global_load_dwordx4 v[68:71], v2, s[6:7] offset:16 nt
	s_add_u32 s6, s6, 0x400000
	s_addc_u32 s7, s7, 0
	s_waitcnt vmcnt(15)
	v_cvt_pk_fp8_f32 v8, v72, v73
	v_cvt_pk_fp8_f32 v9, v74, v75
	v_cvt_pk_fp8_f32 v10, v76, v77
	v_cvt_pk_fp8_f32 v11, v78, v79
	v_and_b32_e32 v8, 0xffff, v8
	v_and_b32_e32 v10, 0xffff, v10
	v_lshl_or_b32 v130, v9, 16, v8
	v_lshl_or_b32 v131, v11, 16, v10
	global_store_dwordx2 v3, v[130:131], s[8:9]
	s_add_u32 s8, s8, 0x100000
	s_addc_u32 s9, s9, 0
	global_load_dwordx4 v[72:75], v2, s[6:7] nt
	global_load_dwordx4 v[76:79], v2, s[6:7] offset:16 nt
	s_add_u32 s6, s6, 0x400000
	s_addc_u32 s7, s7, 0
	s_waitcnt vmcnt(16)
	v_cvt_pk_fp8_f32 v8, v80, v81
	v_cvt_pk_fp8_f32 v9, v82, v83
	v_cvt_pk_fp8_f32 v10, v84, v85
	v_cvt_pk_fp8_f32 v11, v86, v87
	v_and_b32_e32 v8, 0xffff, v8
	v_and_b32_e32 v10, 0xffff, v10
	v_lshl_or_b32 v132, v9, 16, v8
	v_lshl_or_b32 v133, v11, 16, v10
	global_store_dwordx2 v3, v[132:133], s[8:9]
	s_add_u32 s8, s8, 0x100000
	s_addc_u32 s9, s9, 0
	global_load_dwordx4 v[80:83], v2, s[6:7] nt
	global_load_dwordx4 v[84:87], v2, s[6:7] offset:16 nt
	s_add_u32 s6, s6, 0x400000
	s_addc_u32 s7, s7, 0
	s_waitcnt vmcnt(17)
	v_cvt_pk_fp8_f32 v8, v88, v89
	v_cvt_pk_fp8_f32 v9, v90, v91
	v_cvt_pk_fp8_f32 v10, v92, v93
	v_cvt_pk_fp8_f32 v11, v94, v95
	v_and_b32_e32 v8, 0xffff, v8
	v_and_b32_e32 v10, 0xffff, v10
	v_lshl_or_b32 v134, v9, 16, v8
	v_lshl_or_b32 v135, v11, 16, v10
	global_store_dwordx2 v3, v[134:135], s[8:9]
	s_add_u32 s8, s8, 0x100000
	s_addc_u32 s9, s9, 0
	global_load_dwordx4 v[88:91], v2, s[6:7] nt
	global_load_dwordx4 v[92:95], v2, s[6:7] offset:16 nt
	s_add_u32 s6, s6, 0x400000
	s_addc_u32 s7, s7, 0
	s_waitcnt vmcnt(18)
	v_cvt_pk_fp8_f32 v8, v96, v97
	v_cvt_pk_fp8_f32 v9, v98, v99
	v_cvt_pk_fp8_f32 v10, v100, v101
	v_cvt_pk_fp8_f32 v11, v102, v103
	v_and_b32_e32 v8, 0xffff, v8
	v_and_b32_e32 v10, 0xffff, v10
	v_lshl_or_b32 v136, v9, 16, v8
	v_lshl_or_b32 v137, v11, 16, v10
	global_store_dwordx2 v3, v[136:137], s[8:9]
	s_add_u32 s8, s8, 0x100000
	s_addc_u32 s9, s9, 0
	global_load_dwordx4 v[96:99], v2, s[6:7] nt
	global_load_dwordx4 v[100:103], v2, s[6:7] offset:16 nt
	s_add_u32 s6, s6, 0x400000
	s_addc_u32 s7, s7, 0
	s_waitcnt vmcnt(19)
	v_cvt_pk_fp8_f32 v8, v104, v105
	v_cvt_pk_fp8_f32 v9, v106, v107
	v_cvt_pk_fp8_f32 v10, v108, v109
	v_cvt_pk_fp8_f32 v11, v110, v111
	v_and_b32_e32 v8, 0xffff, v8
	v_and_b32_e32 v10, 0xffff, v10
	v_lshl_or_b32 v138, v9, 16, v8
	v_lshl_or_b32 v139, v11, 16, v10
	global_store_dwordx2 v3, v[138:139], s[8:9]
	s_add_u32 s8, s8, 0x100000
	s_addc_u32 s9, s9, 0
	global_load_dwordx4 v[104:107], v2, s[6:7] nt
	global_load_dwordx4 v[108:111], v2, s[6:7] offset:16 nt
	s_add_u32 s6, s6, 0x400000
	s_addc_u32 s7, s7, 0
	s_waitcnt vmcnt(20)
	v_cvt_pk_fp8_f32 v8, v112, v113
	v_cvt_pk_fp8_f32 v9, v114, v115
	v_cvt_pk_fp8_f32 v10, v116, v117
	v_cvt_pk_fp8_f32 v11, v118, v119
	v_and_b32_e32 v8, 0xffff, v8
	v_and_b32_e32 v10, 0xffff, v10
	v_lshl_or_b32 v140, v9, 16, v8
	v_lshl_or_b32 v141, v11, 16, v10
	global_store_dwordx2 v3, v[140:141], s[8:9]
	s_add_u32 s8, s8, 0x100000
	s_addc_u32 s9, s9, 0
	global_load_dwordx4 v[112:115], v2, s[6:7] nt
	global_load_dwordx4 v[116:119], v2, s[6:7] offset:16 nt
	s_add_u32 s6, s6, 0x400000
	s_addc_u32 s7, s7, 0
	s_waitcnt vmcnt(21)
; __device__ __forceinline__ unsigned cvt_pk_bf16(float lo, float hi) { unsigned r; asm volatile("v_cvt_pk_bf16_f32 %0, %1, %2" : "=v"(r) : "v"(lo), "v"(hi)); return r; }
; __global__ void __launch_bounds__(512, 2) hybrid_fwd(Args a) {
;     ...
;             for (size_t i0 = gt; i0 < NCH; i0 += 4 * GT) {
;                 f32x4 v[4][2];
; #pragma unroll
;                 for (int u = 0; u < 4; ++u) { const size_t i = i0 + (size_t)u * GT; if (i < NCH) { v[u][0] = ((const f32x4*)a.x)[2 * i]; v[u][1] = ((const f32x4*)a.x)[2 * i + 1]; } }
; #pragma unroll
;                 for (int u = 0; u < 4; ++u) { const size_t i = i0 + (size_t)u * GT; if (i < NCH) {
;                     u32x4 w; w.x = cvt_pk_bf16(v[u][0][0], v[u][0][1]); w.y = cvt_pk_bf16(v[u][0][2], v[u][0][3]); w.z = cvt_pk_bf16(v[u][1][0], v[u][1][1]); w.w = cvt_pk_bf16(v[u][1][2], v[u][1][3]);
;                     if (a.n_bf16 > 0) ((u32x4*)XB)[i] = w;
;                     const unsigned p0 = pack_fp8x4(v[u][0][0], v[u][0][1], v[u][0][2], v[u][0][3]), p1 = pack_fp8x4(v[u][1][0], v[u][1][1], v[u][1][2], v[u][1][3]);
;                     ((u32x2*)XB8)[i] = (u32x2){p0, p1}; } }
	v_cvt_pk_fp8_f32 v8, v120, v121
	v_cvt_pk_fp8_f32 v9, v122, v123
	v_cvt_pk_fp8_f32 v10, v124, v125
	v_cvt_pk_fp8_f32 v11, v126, v127
	v_and_b32_e32 v8, 0xffff, v8
	v_and_b32_e32 v10, 0xffff, v10
	v_lshl_or_b32 v142, v9, 16, v8
	v_lshl_or_b32 v143, v11, 16, v10
	global_store_dwordx2 v3, v[142:143], s[8:9]
	s_add_u32 s8, s8, 0x100000
	s_addc_u32 s9, s9, 0
	global_load_dwordx4 v[120:123], v2, s[6:7] nt
	global_load_dwordx4 v[124:127], v2, s[6:7] offset:16 nt
	s_add_u32 s6, s6, 0x400000
	s_addc_u32 s7, s7, 0
	s_waitcnt vmcnt(21)
	v_cvt_pk_fp8_f32 v8, v64, v65
	v_cvt_pk_fp8_f32 v9, v66, v67
	v_cvt_pk_fp8_f32 v10, v68, v69
	v_cvt_pk_fp8_f32 v11, v70, v71
	v_and_b32_e32 v8, 0xffff, v8
	v_and_b32_e32 v10, 0xffff, v10
	v_lshl_or_b32 v128, v9, 16, v8
	v_lshl_or_b32 v129, v11, 16, v10
	global_store_dwordx2 v3, v[128:129], s[8:9]
	s_add_u32 s8, s8, 0x100000
	s_addc_u32 s9, s9, 0
	global_load_dwordx4 v[64:67], v2, s[6:7] nt
	global_load_dwordx4 v[68:71], v2, s[6:7] offset:16 nt
	s_add_u32 s6, s6, 0x400000
	s_addc_u32 s7, s7, 0
	s_waitcnt vmcnt(21)
	v_cvt_pk_fp8_f32 v8, v72, v73
	v_cvt_pk_fp8_f32 v9, v74, v75
	v_cvt_pk_fp8_f32 v10, v76, v77
	v_cvt_pk_fp8_f32 v11, v78, v79
	v_and_b32_e32 v8, 0xffff, v8
	v_and_b32_e32 v10, 0xffff, v10
	v_lshl_or_b32 v130, v9, 16, v8
	v_lshl_or_b32 v131, v11, 16, v10
	global_store_dwordx2 v3, v[130:131], s[8:9]
	s_add_u32 s8, s8, 0x100000
	s_addc_u32 s9, s9, 0
	global_load_dwordx4 v[72:75], v2, s[6:7] nt
	global_load_dwordx4 v[76:79], v2, s[6:7] offset:16 nt
	s_add_u32 s6, s6, 0x400000
	s_addc_u32 s7, s7, 0
	s_waitcnt vmcnt(21)
	v_cvt_pk_fp8_f32 v8, v80, v81
	v_cvt_pk_fp8_f32 v9, v82, v83
	v_cvt_pk_fp8_f32 v10, v84, v85
	v_cvt_pk_fp8_f32 v11, v86, v87
	v_and_b32_e32 v8, 0xffff, v8
	v_and_b32_e32 v10, 0xffff, v10
	v_lshl_or_b32 v132, v9, 16, v8
	v_lshl_or_b32 v133, v11, 16, v10
	global_store_dwordx2 v3, v[132:133], s[8:9]
	s_add_u32 s8, s8, 0x100000
	s_addc_u32 s9, s9, 0
	global_load_dwordx4 v[80:83], v2, s[6:7] nt
	global_load_dwordx4 v[84:87], v2, s[6:7] offset:16 nt
	s_add_u32 s6, s6, 0x400000
	s_addc_u32 s7, s7, 0
	s_waitcnt vmcnt(21)
	v_cvt_pk_fp8_f32 v8, v88, v89
	v_cvt_pk_fp8_f32 v9, v90, v91
	v_cvt_pk_fp8_f32 v10, v92, v93
	v_cvt_pk_fp8_f32 v11, v94, v95
	v_and_b32_e32 v8, 0xffff, v8
	v_and_b32_e32 v10, 0xffff, v10
	v_lshl_or_b32 v134, v9, 16, v8
	v_lshl_or_b32 v135, v11, 16, v10
	global_store_dwordx2 v3, v[134:135], s[8:9]
	s_add_u32 s8, s8, 0x100000
	s_addc_u32 s9, s9, 0
	global_load_dwordx4 v[88:91], v2, s[6:7] nt
	global_load_dwordx4 v[92:95], v2, s[6:7] offset:16 nt
	s_add_u32 s6, s6, 0x400000
	s_addc_u32 s7, s7, 0
	s_waitcnt vmcnt(21)
	v_cvt_pk_fp8_f32 v8, v96, v97
	v_cvt_pk_fp8_f32 v9, v98, v99
	v_cvt_pk_fp8_f32 v10, v100, v101
	v_cvt_pk_fp8_f32 v11, v102, v103
	v_and_b32_e32 v8, 0xffff, v8
	v_and_b32_e32 v10, 0xffff, v10
	v_lshl_or_b32 v136, v9, 16, v8
	v_lshl_or_b32 v137, v11, 16, v10
	global_store_dwordx2 v3, v[136:137], s[8:9]
	s_add_u32 s8, s8, 0x100000
	s_addc_u32 s9, s9, 0
	global_load_dwordx4 v[96:99], v2, s[6:7] nt
	global_load_dwordx4 v[100:103], v2, s[6:7] offset:16 nt
	s_add_u32 s6, s6, 0x400000
	s_addc_u32 s7, s7, 0
	s_waitcnt vmcnt(21)
	v_cvt_pk_fp8_f32 v8, v104, v105
	v_cvt_pk_fp8_f32 v9, v106, v107
	v_cvt_pk_fp8_f32 v10, v108, v109
	v_cvt_pk_fp8_f32 v11, v110, v111
	v_and_b32_e32 v8, 0xffff, v8
	v_and_b32_e32 v10, 0xffff, v10
	v_lshl_or_b32 v138, v9, 16, v8
	v_lshl_or_b32 v139, v11, 16, v10
	global_store_dwordx2 v3, v[138:139], s[8:9]
	s_add_u32 s8, s8, 0x100000
	s_addc_u32 s9, s9, 0
	global_load_dwordx4 v[104:107], v2, s[6:7] nt
	global_load_dwordx4 v[108:111], v2, s[6:7] offset:16 nt
	s_add_u32 s6, s6, 0x400000
	s_addc_u32 s7, s7, 0
	s_waitcnt vmcnt(21)
	v_cvt_pk_fp8_f32 v8, v112, v113
	v_cvt_pk_fp8_f32 v9, v114, v115
	v_cvt_pk_fp8_f32 v10, v116, v117
	v_cvt_pk_fp8_f32 v11, v118, v119
	v_and_b32_e32 v8, 0xffff, v8
	v_and_b32_e32 v10, 0xffff, v10
	v_lshl_or_b32 v140, v9, 16, v8
	v_lshl_or_b32 v141, v11, 16, v10
	global_store_dwordx2 v3, v[140:141], s[8:9]
	s_add_u32 s8, s8, 0x100000
	s_addc_u32 s9, s9, 0
	global_load_dwordx4 v[112:115], v2, s[6:7] nt
	global_load_dwordx4 v[116:119], v2, s[6:7] offset:16 nt
	s_add_u32 s6, s6, 0x400000
	s_addc_u32 s7, s7, 0
	s_waitcnt vmcnt(21)
	v_cvt_pk_fp8_f32 v8, v120, v121
	v_cvt_pk_fp8_f32 v9, v122, v123
	v_cvt_pk_fp8_f32 v10, v124, v125
	v_cvt_pk_fp8_f32 v11, v126, v127
	v_and_b32_e32 v8, 0xffff, v8
	v_and_b32_e32 v10, 0xffff, v10
	v_lshl_or_b32 v142, v9, 16, v8
	v_lshl_or_b32 v143, v11, 16, v10
	global_store_dwordx2 v3, v[142:143], s[8:9]
	s_add_u32 s8, s8, 0x100000
	s_addc_u32 s9, s9, 0
	global_load_dwordx4 v[120:123], v2, s[6:7] nt
	global_load_dwordx4 v[124:127], v2, s[6:7] offset:16 nt
	s_add_u32 s6, s6, 0x400000
	s_addc_u32 s7, s7, 0
	s_waitcnt vmcnt(21)
	v_cvt_pk_fp8_f32 v8, v64, v65
	v_cvt_pk_fp8_f32 v9, v66, v67
	v_cvt_pk_fp8_f32 v10, v68, v69
	v_cvt_pk_fp8_f32 v11, v70, v71
	v_and_b32_e32 v8, 0xffff, v8
	v_and_b32_e32 v10, 0xffff, v10
	v_lshl_or_b32 v128, v9, 16, v8
	v_lshl_or_b32 v129, v11, 16, v10
	global_store_dwordx2 v3, v[128:129], s[8:9]
	s_add_u32 s8, s8, 0x100000
	s_addc_u32 s9, s9, 0
	global_load_dwordx4 v[64:67], v2, s[6:7] nt
	global_load_dwordx4 v[68:71], v2, s[6:7] offset:16 nt
	s_add_u32 s6, s6, 0x400000
	s_addc_u32 s7, s7, 0
	s_waitcnt vmcnt(21)
	v_cvt_pk_fp8_f32 v8, v72, v73
	v_cvt_pk_fp8_f32 v9, v74, v75
	v_cvt_pk_fp8_f32 v10, v76, v77
	v_cvt_pk_fp8_f32 v11, v78, v79
	v_and_b32_e32 v8, 0xffff, v8
	v_and_b32_e32 v10, 0xffff, v10
	v_lshl_or_b32 v130, v9, 16, v8
	v_lshl_or_b32 v131, v11, 16, v10
	global_store_dwordx2 v3, v[130:131], s[8:9]
	s_add_u32 s8, s8, 0x100000
	s_addc_u32 s9, s9, 0
	global_load_dwordx4 v[72:75], v2, s[6:7] nt
	global_load_dwordx4 v[76:79], v2, s[6:7] offset:16 nt
	s_add_u32 s6, s6, 0x400000
	s_addc_u32 s7, s7, 0
	s_waitcnt vmcnt(21)
; __device__ __forceinline__ unsigned cvt_pk_bf16(float lo, float hi) { unsigned r; asm volatile("v_cvt_pk_bf16_f32 %0, %1, %2" : "=v"(r) : "v"(lo), "v"(hi)); return r; }
; __global__ void __launch_bounds__(512, 2) hybrid_fwd(Args a) {
;     ...
;             for (size_t i0 = gt; i0 < NCH; i0 += 4 * GT) {
;                 f32x4 v[4][2];
; #pragma unroll
;                 for (int u = 0; u < 4; ++u) { const size_t i = i0 + (size_t)u * GT; if (i < NCH) { v[u][0] = ((const f32x4*)a.x)[2 * i]; v[u][1] = ((const f32x4*)a.x)[2 * i + 1]; } }
; #pragma unroll
;                 for (int u = 0; u < 4; ++u) { const size_t i = i0 + (size_t)u * GT; if (i < NCH) {
;                     u32x4 w; w.x = cvt_pk_bf16(v[u][0][0], v[u][0][1]); w.y = cvt_pk_bf16(v[u][0][2], v[u][0][3]); w.z = cvt_pk_bf16(v[u][1][0], v[u][1][1]); w.w = cvt_pk_bf16(v[u][1][2], v[u][1][3]);
;                     if (a.n_bf16 > 0) ((u32x4*)XB)[i] = w;
;                     const unsigned p0 = pack_fp8x4(v[u][0][0], v[u][0][1], v[u][0][2], v[u][0][3]), p1 = pack_fp8x4(v[u][1][0], v[u][1][1], v[u][1][2], v[u][1][3]);
;                     ((u32x2*)XB8)[i] = (u32x2){p0, p1}; } }
	v_cvt_pk_fp8_f32 v8, v80, v81
	v_cvt_pk_fp8_f32 v9, v82, v83
	v_cvt_pk_fp8_f32 v10, v84, v85
	v_cvt_pk_fp8_f32 v11, v86, v87
	v_and_b32_e32 v8, 0xffff, v8
	v_and_b32_e32 v10, 0xffff, v10
	v_lshl_or_b32 v132, v9, 16, v8
	v_lshl_or_b32 v133, v11, 16, v10
	global_store_dwordx2 v3, v[132:133], s[8:9]
	s_add_u32 s8, s8, 0x100000
	s_addc_u32 s9, s9, 0
	global_load_dwordx4 v[80:83], v2, s[6:7] nt
	global_load_dwordx4 v[84:87], v2, s[6:7] offset:16 nt
	s_add_u32 s6, s6, 0x400000
	s_addc_u32 s7, s7, 0
	s_waitcnt vmcnt(21)
	v_cvt_pk_fp8_f32 v8, v88, v89
	v_cvt_pk_fp8_f32 v9, v90, v91
	v_cvt_pk_fp8_f32 v10, v92, v93
	v_cvt_pk_fp8_f32 v11, v94, v95
	v_and_b32_e32 v8, 0xffff, v8
	v_and_b32_e32 v10, 0xffff, v10
	v_lshl_or_b32 v134, v9, 16, v8
	v_lshl_or_b32 v135, v11, 16, v10
	global_store_dwordx2 v3, v[134:135], s[8:9]
	s_add_u32 s8, s8, 0x100000
	s_addc_u32 s9, s9, 0
	global_load_dwordx4 v[88:91], v2, s[6:7] nt
	global_load_dwordx4 v[92:95], v2, s[6:7] offset:16 nt
	s_add_u32 s6, s6, 0x400000
	s_addc_u32 s7, s7, 0
	s_waitcnt vmcnt(21)
	v_cvt_pk_fp8_f32 v8, v96, v97
	v_cvt_pk_fp8_f32 v9, v98, v99
	v_cvt_pk_fp8_f32 v10, v100, v101
	v_cvt_pk_fp8_f32 v11, v102, v103
	v_and_b32_e32 v8, 0xffff, v8
	v_and_b32_e32 v10, 0xffff, v10
	v_lshl_or_b32 v136, v9, 16, v8
	v_lshl_or_b32 v137, v11, 16, v10
	global_store_dwordx2 v3, v[136:137], s[8:9]
	s_add_u32 s8, s8, 0x100000
	s_addc_u32 s9, s9, 0
	global_load_dwordx4 v[96:99], v2, s[6:7] nt
	global_load_dwordx4 v[100:103], v2, s[6:7] offset:16 nt
	s_add_u32 s6, s6, 0x400000
	s_addc_u32 s7, s7, 0
	s_waitcnt vmcnt(21)
	v_cvt_pk_fp8_f32 v8, v104, v105
	v_cvt_pk_fp8_f32 v9, v106, v107
	v_cvt_pk_fp8_f32 v10, v108, v109
	v_cvt_pk_fp8_f32 v11, v110, v111
	v_and_b32_e32 v8, 0xffff, v8
	v_and_b32_e32 v10, 0xffff, v10
	v_lshl_or_b32 v138, v9, 16, v8
	v_lshl_or_b32 v139, v11, 16, v10
	global_store_dwordx2 v3, v[138:139], s[8:9]
	s_add_u32 s8, s8, 0x100000
	s_addc_u32 s9, s9, 0
	global_load_dwordx4 v[104:107], v2, s[6:7] nt
	global_load_dwordx4 v[108:111], v2, s[6:7] offset:16 nt
	s_add_u32 s6, s6, 0x400000
	s_addc_u32 s7, s7, 0
	s_waitcnt vmcnt(21)
	v_cvt_pk_fp8_f32 v8, v112, v113
	v_cvt_pk_fp8_f32 v9, v114, v115
	v_cvt_pk_fp8_f32 v10, v116, v117
	v_cvt_pk_fp8_f32 v11, v118, v119
	v_and_b32_e32 v8, 0xffff, v8
	v_and_b32_e32 v10, 0xffff, v10
	v_lshl_or_b32 v140, v9, 16, v8
	v_lshl_or_b32 v141, v11, 16, v10
	global_store_dwordx2 v3, v[140:141], s[8:9]
	s_add_u32 s8, s8, 0x100000
	s_addc_u32 s9, s9, 0
	global_load_dwordx4 v[112:115], v2, s[6:7] nt
	global_load_dwordx4 v[116:119], v2, s[6:7] offset:16 nt
	s_add_u32 s6, s6, 0x400000
	s_addc_u32 s7, s7, 0
	s_waitcnt vmcnt(21)
	v_cvt_pk_fp8_f32 v8, v120, v121
	v_cvt_pk_fp8_f32 v9, v122, v123
	v_cvt_pk_fp8_f32 v10, v124, v125
	v_cvt_pk_fp8_f32 v11, v126, v127
	v_and_b32_e32 v8, 0xffff, v8
	v_and_b32_e32 v10, 0xffff, v10
	v_lshl_or_b32 v142, v9, 16, v8
	v_lshl_or_b32 v143, v11, 16, v10
	global_store_dwordx2 v3, v[142:143], s[8:9]
	s_add_u32 s8, s8, 0x100000
	s_addc_u32 s9, s9, 0
	global_load_dwordx4 v[120:123], v2, s[6:7] nt
	global_load_dwordx4 v[124:127], v2, s[6:7] offset:16 nt
	s_add_u32 s6, s6, 0x400000
	s_addc_u32 s7, s7, 0
	s_waitcnt vmcnt(21)
	v_cvt_pk_fp8_f32 v8, v64, v65
	v_cvt_pk_fp8_f32 v9, v66, v67
	v_cvt_pk_fp8_f32 v10, v68, v69
	v_cvt_pk_fp8_f32 v11, v70, v71
	v_and_b32_e32 v8, 0xffff, v8
	v_and_b32_e32 v10, 0xffff, v10
	v_lshl_or_b32 v128, v9, 16, v8
	v_lshl_or_b32 v129, v11, 16, v10
	global_store_dwordx2 v3, v[128:129], s[8:9]
	s_add_u32 s8, s8, 0x100000
	s_addc_u32 s9, s9, 0
	s_waitcnt vmcnt(19)
	v_cvt_pk_fp8_f32 v8, v72, v73
	v_cvt_pk_fp8_f32 v9, v74, v75
	v_cvt_pk_fp8_f32 v10, v76, v77
	v_cvt_pk_fp8_f32 v11, v78, v79
	v_and_b32_e32 v8, 0xffff, v8
	v_and_b32_e32 v10, 0xffff, v10
	v_lshl_or_b32 v130, v9, 16, v8
	v_lshl_or_b32 v131, v11, 16, v10
	global_store_dwordx2 v3, v[130:131], s[8:9]
	s_add_u32 s8, s8, 0x100000
	s_addc_u32 s9, s9, 0
	s_waitcnt vmcnt(17)
	v_cvt_pk_fp8_f32 v8, v80, v81
	v_cvt_pk_fp8_f32 v9, v82, v83
	v_cvt_pk_fp8_f32 v10, v84, v85
	v_cvt_pk_fp8_f32 v11, v86, v87
	v_and_b32_e32 v8, 0xffff, v8
	v_and_b32_e32 v10, 0xffff, v10
	v_lshl_or_b32 v132, v9, 16, v8
	v_lshl_or_b32 v133, v11, 16, v10
	global_store_dwordx2 v3, v[132:133], s[8:9]
	s_add_u32 s8, s8, 0x100000
	s_addc_u32 s9, s9, 0
	s_waitcnt vmcnt(15)
	v_cvt_pk_fp8_f32 v8, v88, v89
	v_cvt_pk_fp8_f32 v9, v90, v91
	v_cvt_pk_fp8_f32 v10, v92, v93
	v_cvt_pk_fp8_f32 v11, v94, v95
	v_and_b32_e32 v8, 0xffff, v8
	v_and_b32_e32 v10, 0xffff, v10
	v_lshl_or_b32 v134, v9, 16, v8
	v_lshl_or_b32 v135, v11, 16, v10
	global_store_dwordx2 v3, v[134:135], s[8:9]
	s_add_u32 s8, s8, 0x100000
	s_addc_u32 s9, s9, 0
	s_waitcnt vmcnt(13)
	v_cvt_pk_fp8_f32 v8, v96, v97
	v_cvt_pk_fp8_f32 v9, v98, v99
	v_cvt_pk_fp8_f32 v10, v100, v101
	v_cvt_pk_fp8_f32 v11, v102, v103
	v_and_b32_e32 v8, 0xffff, v8
	v_and_b32_e32 v10, 0xffff, v10
	v_lshl_or_b32 v136, v9, 16, v8
	v_lshl_or_b32 v137, v11, 16, v10
	global_store_dwordx2 v3, v[136:137], s[8:9]
	s_add_u32 s8, s8, 0x100000
	s_addc_u32 s9, s9, 0
	s_waitcnt vmcnt(11)
	v_cvt_pk_fp8_f32 v8, v104, v105
	v_cvt_pk_fp8_f32 v9, v106, v107
	v_cvt_pk_fp8_f32 v10, v108, v109
	v_cvt_pk_fp8_f32 v11, v110, v111
	v_and_b32_e32 v8, 0xffff, v8
	v_and_b32_e32 v10, 0xffff, v10
	v_lshl_or_b32 v138, v9, 16, v8
	v_lshl_or_b32 v139, v11, 16, v10
	global_store_dwordx2 v3, v[138:139], s[8:9]
	s_add_u32 s8, s8, 0x100000
	s_addc_u32 s9, s9, 0
	s_waitcnt vmcnt(9)
	v_cvt_pk_fp8_f32 v8, v112, v113
	v_cvt_pk_fp8_f32 v9, v114, v115
	v_cvt_pk_fp8_f32 v10, v116, v117
	v_cvt_pk_fp8_f32 v11, v118, v119
	v_and_b32_e32 v8, 0xffff, v8
	v_and_b32_e32 v10, 0xffff, v10
	v_lshl_or_b32 v140, v9, 16, v8
	v_lshl_or_b32 v141, v11, 16, v10
	global_store_dwordx2 v3, v[140:141], s[8:9]
	s_add_u32 s8, s8, 0x100000
	s_addc_u32 s9, s9, 0
	s_waitcnt vmcnt(7)
; #define LAS __attribute__((address_space(3)))
; __device__ __forceinline__ void transpose_item_fp8(const float* W, int N, unsigned char* W8, int pitch, int kofs, int k0, int n_src, int n_dst, float scale, LAS float* scr, int lane) {
;     const int r8 = lane >> 3, c4 = lane & 7;
;     f32x4 v[8];
; #pragma unroll
;     for (int i = 0; i < 8; ++i) v[i] = *(const f32x4*)(W + (size_t)(k0 + r8 + 8 * i) * N + n_src + 4 * c4);
; #pragma unroll
;     for (int i = 0; i < 8; ++i) { LAS float* d = scr + (r8 + 8 * i) * 33 + 4 * c4; d[0] = v[i][0]; d[1] = v[i][1]; d[2] = v[i][2]; d[3] = v[i][3]; }
; __global__ void __launch_bounds__(512, 2) hybrid_fwd(Args a) {
;     ...
;         for (size_t i = gt; i < (size_t)M * 64; i += GT) {
;             const int t = (int)(i >> 6), j = (int)(i & 63);
;             const float ang = (float)a.pos[t] * a.inv_freq[j];
;             const double rev = (double)ang * 0.15915494309189535; const float fr = (float)(rev - __builtin_rint(rev));
;             const f32x2 cs = (f32x2){__builtin_amdgcn_cosf(fr), __builtin_amdgcn_sinf(fr)};
;             csB[i] = cs; if ((j & 1) == 0) csA[(size_t)t * 32 + (j >> 1)] = cs;
;         }
	v_cvt_pk_fp8_f32 v8, v120, v121
	v_cvt_pk_fp8_f32 v9, v122, v123
	v_cvt_pk_fp8_f32 v10, v124, v125
	v_cvt_pk_fp8_f32 v11, v126, v127
	v_and_b32_e32 v8, 0xffff, v8
	v_and_b32_e32 v10, 0xffff, v10
	v_lshl_or_b32 v142, v9, 16, v8
	v_lshl_or_b32 v143, v11, 16, v10
	global_store_dwordx2 v3, v[142:143], s[8:9]
	s_add_u32 s8, s8, 0x100000
	s_addc_u32 s9, s9, 0
	s_lshr_b32 s10, s33, 6
	s_lshl_b32 s11, s2, 3
	s_add_u32 s10, s10, s11
	s_lshl_b32 s11, s10, 2
	s_add_u32 s24, s20, s11
	s_addc_u32 s25, s21, 0
	s_load_dword s34, s[24:25], 0x0
	s_load_dword s35, s[24:25], 0x2000
	s_load_dword s36, s[24:25], 0x4000
	s_load_dword s37, s[24:25], 0x6000
	s_load_dword s38, s[24:25], 0x8000
	s_load_dword s39, s[24:25], 0xa000
	s_load_dword s40, s[24:25], 0xc000
	s_load_dword s41, s[24:25], 0xe000
	v_lshlrev_b32_e32 v5, 2, v4
	global_load_dword v5, v5, s[70:71] offset:96
	v_lshlrev_b32_e32 v6, 3, v4
	v_lshrrev_b32_e32 v7, 1, v4
	v_lshlrev_b32_e32 v7, 3, v7
	s_lshl_b32 s11, s10, 9
	s_add_u32 s26, s90, s11
	s_addc_u32 s27, s91, 0
	s_add_u32 s26, s26, 0x7c00000
	s_addc_u32 s27, s27, 0
	s_lshl_b32 s11, s10, 8
	s_add_u32 s28, s90, s11
	s_addc_u32 s29, s91, 0
	s_add_u32 s28, s28, 0x8400000
	s_addc_u32 s29, s29, 0
	s_mov_b32 s42, 0x6dc9c883
	s_mov_b32 s43, 0x3fc45f30
	s_waitcnt vmcnt(0) lgkmcnt(0)
	v_cvt_f32_i32_e32 v16, s34
	v_mul_f32_e32 v16, v5, v16
	v_cvt_f64_f32_e32 v[16:17], v16
	v_mul_f64 v[12:13], v[16:17], s[42:43]
	v_rndne_f64_e32 v[12:13], v[12:13]
	v_fma_f64 v[16:17], v[16:17], s[42:43], -v[12:13]
	v_cvt_f32_f64_e32 v17, v[16:17]
	v_cos_f32_e32 v16, v17
	v_sin_f32_e32 v17, v17
	v_cvt_f32_i32_e32 v18, s35
	v_mul_f32_e32 v18, v5, v18
	v_cvt_f64_f32_e32 v[18:19], v18
	v_mul_f64 v[12:13], v[18:19], s[42:43]
	v_rndne_f64_e32 v[12:13], v[12:13]
	v_fma_f64 v[18:19], v[18:19], s[42:43], -v[12:13]
	v_cvt_f32_f64_e32 v19, v[18:19]
	v_cos_f32_e32 v18, v19
	v_sin_f32_e32 v19, v19
	v_cvt_f32_i32_e32 v20, s36
	v_mul_f32_e32 v20, v5, v20
	v_cvt_f64_f32_e32 v[20:21], v20
	v_mul_f64 v[12:13], v[20:21], s[42:43]
	v_rndne_f64_e32 v[12:13], v[12:13]
	v_fma_f64 v[20:21], v[20:21], s[42:43], -v[12:13]
	v_cvt_f32_f64_e32 v21, v[20:21]
	v_cos_f32_e32 v20, v21
	v_sin_f32_e32 v21, v21
	v_cvt_f32_i32_e32 v22, s37
	v_mul_f32_e32 v22, v5, v22
	v_cvt_f64_f32_e32 v[22:23], v22
	v_mul_f64 v[12:13], v[22:23], s[42:43]
	v_rndne_f64_e32 v[12:13], v[12:13]
	v_fma_f64 v[22:23], v[22:23], s[42:43], -v[12:13]
	v_cvt_f32_f64_e32 v23, v[22:23]
	v_cos_f32_e32 v22, v23
	v_sin_f32_e32 v23, v23
	v_cvt_f32_i32_e32 v24, s38
	v_mul_f32_e32 v24, v5, v24
	v_cvt_f64_f32_e32 v[24:25], v24
	v_mul_f64 v[12:13], v[24:25], s[42:43]
	v_rndne_f64_e32 v[12:13], v[12:13]
	v_fma_f64 v[24:25], v[24:25], s[42:43], -v[12:13]
	v_cvt_f32_f64_e32 v25, v[24:25]
	v_cos_f32_e32 v24, v25
	v_sin_f32_e32 v25, v25
	v_cvt_f32_i32_e32 v26, s39
	v_mul_f32_e32 v26, v5, v26
	v_cvt_f64_f32_e32 v[26:27], v26
	v_mul_f64 v[12:13], v[26:27], s[42:43]
	v_rndne_f64_e32 v[12:13], v[12:13]
	v_fma_f64 v[26:27], v[26:27], s[42:43], -v[12:13]
	v_cvt_f32_f64_e32 v27, v[26:27]
	v_cos_f32_e32 v26, v27
	v_sin_f32_e32 v27, v27
	v_cvt_f32_i32_e32 v28, s40
	v_mul_f32_e32 v28, v5, v28
	v_cvt_f64_f32_e32 v[28:29], v28
	v_mul_f64 v[12:13], v[28:29], s[42:43]
	v_rndne_f64_e32 v[12:13], v[12:13]
	v_fma_f64 v[28:29], v[28:29], s[42:43], -v[12:13]
	v_cvt_f32_f64_e32 v29, v[28:29]
	v_cos_f32_e32 v28, v29
	v_sin_f32_e32 v29, v29
	v_cvt_f32_i32_e32 v30, s41
	v_mul_f32_e32 v30, v5, v30
	v_cvt_f64_f32_e32 v[30:31], v30
	v_mul_f64 v[12:13], v[30:31], s[42:43]
	v_rndne_f64_e32 v[12:13], v[12:13]
	v_fma_f64 v[30:31], v[30:31], s[42:43], -v[12:13]
	v_cvt_f32_f64_e32 v31, v[30:31]
	v_cos_f32_e32 v30, v31
	v_sin_f32_e32 v31, v31
	s_nop 1
	global_store_dwordx2 v6, v[16:17], s[26:27]
	s_add_u32 s26, s26, 0x100000
	s_addc_u32 s27, s27, 0
	global_store_dwordx2 v6, v[18:19], s[26:27]
	s_add_u32 s26, s26, 0x100000
	s_addc_u32 s27, s27, 0
	global_store_dwordx2 v6, v[20:21], s[26:27]
	s_add_u32 s26, s26, 0x100000
	s_addc_u32 s27, s27, 0
	global_store_dwordx2 v6, v[22:23], s[26:27]
	s_add_u32 s26, s26, 0x100000
	s_addc_u32 s27, s27, 0
	global_store_dwordx2 v6, v[24:25], s[26:27]
	s_add_u32 s26, s26, 0x100000
	s_addc_u32 s27, s27, 0
	global_store_dwordx2 v6, v[26:27], s[26:27]
	s_add_u32 s26, s26, 0x100000
	s_addc_u32 s27, s27, 0
	global_store_dwordx2 v6, v[28:29], s[26:27]
	s_add_u32 s26, s26, 0x100000
	s_addc_u32 s27, s27, 0
	global_store_dwordx2 v6, v[30:31], s[26:27]
	s_mov_b32 exec_lo, 0x55555555
	s_mov_b32 exec_hi, 0x55555555
	s_nop 1
	global_store_dwordx2 v7, v[16:17], s[28:29]
	s_add_u32 s28, s28, 0x80000
	s_addc_u32 s29, s29, 0
	global_store_dwordx2 v7, v[18:19], s[28:29]
	s_add_u32 s28, s28, 0x80000
	s_addc_u32 s29, s29, 0
	global_store_dwordx2 v7, v[20:21], s[28:29]
	s_add_u32 s28, s28, 0x80000
	s_addc_u32 s29, s29, 0
	global_store_dwordx2 v7, v[22:23], s[28:29]
	s_add_u32 s28, s28, 0x80000
	s_addc_u32 s29, s29, 0
	global_store_dwordx2 v7, v[24:25], s[28:29]
	s_add_u32 s28, s28, 0x80000
	s_addc_u32 s29, s29, 0
	global_store_dwordx2 v7, v[26:27], s[28:29]
	s_add_u32 s28, s28, 0x80000
	s_addc_u32 s29, s29, 0
	global_store_dwordx2 v7, v[28:29], s[28:29]
	s_add_u32 s28, s28, 0x80000
	s_addc_u32 s29, s29, 0
	global_store_dwordx2 v7, v[30:31], s[28:29]
	s_mov_b64 exec, -1
	s_nop 1
	v_and_b32_e32 v12, 7, v4
	v_lshrrev_b32_e32 v13, 3, v4
	v_lshlrev_b32_e32 v14, 4, v12
	s_mov_b32 s10, 0x5a000
	v_mul_lo_u32 v15, v13, s10
	v_add_u32_e32 v162, v15, v14
	v_add_u32_e32 v163, 0xb400, v162
	v_add_u32_e32 v164, 0x16800, v162
	v_add_u32_e32 v165, 0x21c00, v162
	v_add_u32_e32 v166, 0x2d000, v162
	v_add_u32_e32 v167, 0x38400, v162
	v_add_u32_e32 v168, 0x43800, v162
	v_add_u32_e32 v169, 0x4ec00, v162
	v_lshlrev_b32_e32 v14, 14, v12
	v_lshl_add_u32 v170, v13, 3, v14
	v_add_u32_e32 v171, 0x1000, v170
	v_add_u32_e32 v172, 0x2000, v170
	v_add_u32_e32 v173, 0x3000, v170
	s_mov_b32 s44, 0x42800000
	s_mov_b32 s45, 0x42800000
	s_lshr_b32 s10, s33, 6
	s_lshl_b32 s11, s2, 3
	s_add_u32 s46, s10, s11
	s_add_u32 s64, s90, 0x4000000
	s_addc_u32 s65, s91, 0
	s_cmpk_ge_u32 s46, 0x680
	s_cbranch_scc1 .Lp0c_four
; #define LAS __attribute__((address_space(3)))
; __host__ __device__ __forceinline__ int tile_mode(int pn) { return (pn <= 4) ? 1 : (pn >= 9 && pn <= 20) ? 2 : 0; }
; __host__ __device__ __forceinline__ int gemm_col_to_orig(int nprime) {
;     const int pn = nprime >> 8, xp = nprime & 255, bj = xp >> 7, x = xp & 127, md = tile_mode(pn);
;     if (md == 1) return 256 * pn + 64 * (x >> 5) + (x & 31) + 32 * bj;
;     if (md == 2) return 256 * pn + 128 * (x >> 6) + (x & 63) + 64 * bj;
;     return nprime;
; }
; __device__ __forceinline__ void transpose_item_fp8(const float* W, int N, unsigned char* W8, int pitch, int kofs, int k0, int n_src, int n_dst, float scale, LAS float* scr, int lane) {
;     const int r8 = lane >> 3, c4 = lane & 7;
;     f32x4 v[8];
; #pragma unroll
;     for (int i = 0; i < 8; ++i) v[i] = *(const f32x4*)(W + (size_t)(k0 + r8 + 8 * i) * N + n_src + 4 * c4);
; #pragma unroll
;     for (int i = 0; i < 8; ++i) { LAS float* d = scr + (r8 + 8 * i) * 33 + 4 * c4; d[0] = v[i][0]; d[1] = v[i][1]; d[2] = v[i][2]; d[3] = v[i][3]; }
;     asm volatile("s_waitcnt lgkmcnt(0)" ::: "memory");
;     const int n = lane & 31, cp = lane >> 5;
; #pragma unroll
;     for (int q = 0; q < 2; ++q) { const int ck = (2 * cp + q) * 16; const LAS float* sp = scr + ck * 33 + n; u32x4 o;
; #pragma unroll
;         for (int w = 0; w < 4; ++w) o[w] = pack_fp8x4(sp[(4 * w) * 33] * scale, sp[(4 * w + 1) * 33] * scale, sp[(4 * w + 2) * 33] * scale, sp[(4 * w + 3) * 33] * scale);
;         *(u32x4*)(W8 + (size_t)(n_dst + n) * pitch + kofs + k0 + ck) = o; }
	s_add_u32 s47, s46, 0x0
	s_mul_hi_u32 s48, s47, 0xb60b61
	s_mul_i32 s49, s48, 0x168
	s_sub_u32 s49, s47, s49
	s_lshl_b32 s50, s48, 1
	s_lshr_b32 s51, s49, 3
	s_and_b32 s52, s49, 7
	s_and_b32 s53, s52, 3
	s_lshr_b32 s54, s52, 2
	s_lshl_b32 s55, s53, 6
	s_lshl_b32 s56, s54, 5
	s_add_u32 s55, s55, s56
	s_bfe_u32 s56, s52, 0x10001
	s_lshl_b32 s56, s56, 7
	s_and_b32 s57, s52, 1
	s_lshl_b32 s57, s57, 5
	s_add_u32 s56, s56, s57
	s_lshl_b32 s57, s54, 6
	s_add_u32 s56, s56, s57
	s_lshl_b32 s57, s52, 5
	s_sub_u32 s58, s51, 9
	s_cmp_lt_u32 s58, 12
	s_cselect_b32 s57, s56, s57
	s_cmp_lt_u32 s51, 5
	s_cselect_b32 s57, s55, s57
	s_lshl_b32 s58, s51, 8
	s_add_u32 s57, s57, s58
	s_mul_i32 s58, s50, 0x2d0000
	s_lshl_b32 s57, s57, 2
	s_add_u32 s58, s58, s57
	s_add_u32 s60, s22, s58
	s_addc_u32 s61, s23, 0
	s_lshl_b32 s58, s49, 17
	s_lshl_b32 s59, s50, 6
	s_add_u32 s58, s58, s59
	s_add_u32 s74, s64, s58
	s_addc_u32 s75, s65, 0
	global_load_dwordx4 v[64:67], v162, s[60:61] nt
	global_load_dwordx4 v[68:71], v163, s[60:61] nt
	global_load_dwordx4 v[72:75], v164, s[60:61] nt
	global_load_dwordx4 v[76:79], v165, s[60:61] nt
	global_load_dwordx4 v[80:83], v166, s[60:61] nt
	global_load_dwordx4 v[84:87], v167, s[60:61] nt
	global_load_dwordx4 v[88:91], v168, s[60:61] nt
	global_load_dwordx4 v[92:95], v169, s[60:61] nt
	s_add_u32 s47, s46, 0x0
	s_mul_hi_u32 s48, s47, 0xb60b61
	s_mul_i32 s49, s48, 0x168
	s_sub_u32 s49, s47, s49
	s_lshl_b32 s50, s48, 1
	s_or_b32 s50, s50, 1
	s_lshr_b32 s51, s49, 3
	s_and_b32 s52, s49, 7
	s_and_b32 s53, s52, 3
	s_lshr_b32 s54, s52, 2
	s_lshl_b32 s55, s53, 6
	s_lshl_b32 s56, s54, 5
	s_add_u32 s55, s55, s56
	s_bfe_u32 s56, s52, 0x10001
	s_lshl_b32 s56, s56, 7
	s_and_b32 s57, s52, 1
	s_lshl_b32 s57, s57, 5
	s_add_u32 s56, s56, s57
	s_lshl_b32 s57, s54, 6
	s_add_u32 s56, s56, s57
	s_lshl_b32 s57, s52, 5
	s_sub_u32 s58, s51, 9
	s_cmp_lt_u32 s58, 12
	s_cselect_b32 s57, s56, s57
	s_cmp_lt_u32 s51, 5
	s_cselect_b32 s57, s55, s57
	s_lshl_b32 s58, s51, 8
	s_add_u32 s57, s57, s58
	s_mul_i32 s58, s50, 0x2d0000
	s_lshl_b32 s57, s57, 2
	s_add_u32 s58, s58, s57
	s_add_u32 s60, s22, s58
	s_addc_u32 s61, s23, 0
	s_lshl_b32 s58, s49, 17
	s_lshl_b32 s59, s50, 6
	s_add_u32 s58, s58, s59
	s_add_u32 s76, s64, s58
	s_addc_u32 s77, s65, 0
	global_load_dwordx4 v[96:99], v162, s[60:61] nt
	global_load_dwordx4 v[100:103], v163, s[60:61] nt
	global_load_dwordx4 v[104:107], v164, s[60:61] nt
	global_load_dwordx4 v[108:111], v165, s[60:61] nt
	global_load_dwordx4 v[112:115], v166, s[60:61] nt
	global_load_dwordx4 v[116:119], v167, s[60:61] nt
	global_load_dwordx4 v[120:123], v168, s[60:61] nt
	global_load_dwordx4 v[124:127], v169, s[60:61] nt
	s_add_u32 s47, s46, 0x800
	s_mul_hi_u32 s48, s47, 0xb60b61
	s_mul_i32 s49, s48, 0x168
	s_sub_u32 s49, s47, s49
	s_lshl_b32 s50, s48, 1
	s_lshr_b32 s51, s49, 3
	s_and_b32 s52, s49, 7
	s_and_b32 s53, s52, 3
	s_lshr_b32 s54, s52, 2
	s_lshl_b32 s55, s53, 6
	s_lshl_b32 s56, s54, 5
	s_add_u32 s55, s55, s56
	s_bfe_u32 s56, s52, 0x10001
	s_lshl_b32 s56, s56, 7
	s_and_b32 s57, s52, 1
	s_lshl_b32 s57, s57, 5
	s_add_u32 s56, s56, s57
	s_lshl_b32 s57, s54, 6
	s_add_u32 s56, s56, s57
	s_lshl_b32 s57, s52, 5
	s_sub_u32 s58, s51, 9
	s_cmp_lt_u32 s58, 12
	s_cselect_b32 s57, s56, s57
	s_cmp_lt_u32 s51, 5
	s_cselect_b32 s57, s55, s57
	s_lshl_b32 s58, s51, 8
	s_add_u32 s57, s57, s58
	s_mul_i32 s58, s50, 0x2d0000
	s_lshl_b32 s57, s57, 2
	s_add_u32 s58, s58, s57
	s_add_u32 s60, s22, s58
	s_addc_u32 s61, s23, 0
	s_lshl_b32 s58, s49, 17
	s_lshl_b32 s59, s50, 6
	s_add_u32 s58, s58, s59
	s_add_u32 s78, s64, s58
	s_addc_u32 s79, s65, 0
	global_load_dwordx4 v[128:131], v162, s[60:61] nt
	global_load_dwordx4 v[132:135], v163, s[60:61] nt
	global_load_dwordx4 v[136:139], v164, s[60:61] nt
	global_load_dwordx4 v[140:143], v165, s[60:61] nt
	global_load_dwordx4 v[144:147], v166, s[60:61] nt
	global_load_dwordx4 v[148:151], v167, s[60:61] nt
	global_load_dwordx4 v[152:155], v168, s[60:61] nt
	global_load_dwordx4 v[156:159], v169, s[60:61] nt
	s_waitcnt vmcnt(16)
	v_pk_mul_f32 v[64:65], v[64:65], s[44:45]
	v_pk_mul_f32 v[66:67], v[66:67], s[44:45]
	v_pk_mul_f32 v[68:69], v[68:69], s[44:45]
	v_pk_mul_f32 v[70:71], v[70:71], s[44:45]
	v_pk_mul_f32 v[72:73], v[72:73], s[44:45]
	v_pk_mul_f32 v[74:75], v[74:75], s[44:45]
	v_pk_mul_f32 v[76:77], v[76:77], s[44:45]
	v_pk_mul_f32 v[78:79], v[78:79], s[44:45]
	v_pk_mul_f32 v[80:81], v[80:81], s[44:45]
	v_pk_mul_f32 v[82:83], v[82:83], s[44:45]
	v_pk_mul_f32 v[84:85], v[84:85], s[44:45]
	v_pk_mul_f32 v[86:87], v[86:87], s[44:45]
	v_pk_mul_f32 v[88:89], v[88:89], s[44:45]
	v_pk_mul_f32 v[90:91], v[90:91], s[44:45]
	v_pk_mul_f32 v[92:93], v[92:93], s[44:45]
	v_pk_mul_f32 v[94:95], v[94:95], s[44:45]
	v_cvt_pk_fp8_f32 v8, v64, v68
	v_cvt_pk_fp8_f32 v9, v72, v76
	v_cvt_pk_fp8_f32 v10, v80, v84
	v_cvt_pk_fp8_f32 v11, v88, v92
	v_and_b32_e32 v8, 0xffff, v8
	v_and_b32_e32 v10, 0xffff, v10
	v_lshl_or_b32 v176, v9, 16, v8
	v_lshl_or_b32 v177, v11, 16, v10
	global_store_dwordx2 v170, v[176:177], s[74:75]
	v_cvt_pk_fp8_f32 v8, v65, v69
	v_cvt_pk_fp8_f32 v9, v73, v77
	v_cvt_pk_fp8_f32 v10, v81, v85
	v_cvt_pk_fp8_f32 v11, v89, v93
	v_and_b32_e32 v8, 0xffff, v8
	v_and_b32_e32 v10, 0xffff, v10
	v_lshl_or_b32 v178, v9, 16, v8
	v_lshl_or_b32 v179, v11, 16, v10
	global_store_dwordx2 v171, v[178:179], s[74:75]
	v_cvt_pk_fp8_f32 v8, v66, v70
	v_cvt_pk_fp8_f32 v9, v74, v78
	v_cvt_pk_fp8_f32 v10, v82, v86
	v_cvt_pk_fp8_f32 v11, v90, v94
	v_and_b32_e32 v8, 0xffff, v8
	v_and_b32_e32 v10, 0xffff, v10
	v_lshl_or_b32 v180, v9, 16, v8
	v_lshl_or_b32 v181, v11, 16, v10
	global_store_dwordx2 v172, v[180:181], s[74:75]
	v_cvt_pk_fp8_f32 v8, v67, v71
; #define LAS __attribute__((address_space(3)))
; __host__ __device__ __forceinline__ int tile_mode(int pn) { return (pn <= 4) ? 1 : (pn >= 9 && pn <= 20) ? 2 : 0; }
; __host__ __device__ __forceinline__ int gemm_col_to_orig(int nprime) {
;     const int pn = nprime >> 8, xp = nprime & 255, bj = xp >> 7, x = xp & 127, md = tile_mode(pn);
;     if (md == 1) return 256 * pn + 64 * (x >> 5) + (x & 31) + 32 * bj;
;     if (md == 2) return 256 * pn + 128 * (x >> 6) + (x & 63) + 64 * bj;
;     return nprime;
; }
; __device__ __forceinline__ void transpose_item_fp8(const float* W, int N, unsigned char* W8, int pitch, int kofs, int k0, int n_src, int n_dst, float scale, LAS float* scr, int lane) {
;     const int r8 = lane >> 3, c4 = lane & 7;
;     f32x4 v[8];
; #pragma unroll
;     for (int i = 0; i < 8; ++i) v[i] = *(const f32x4*)(W + (size_t)(k0 + r8 + 8 * i) * N + n_src + 4 * c4);
; #pragma unroll
;     for (int i = 0; i < 8; ++i) { LAS float* d = scr + (r8 + 8 * i) * 33 + 4 * c4; d[0] = v[i][0]; d[1] = v[i][1]; d[2] = v[i][2]; d[3] = v[i][3]; }
;     asm volatile("s_waitcnt lgkmcnt(0)" ::: "memory");
;     const int n = lane & 31, cp = lane >> 5;
; #pragma unroll
;     for (int q = 0; q < 2; ++q) { const int ck = (2 * cp + q) * 16; const LAS float* sp = scr + ck * 33 + n; u32x4 o;
; #pragma unroll
;         for (int w = 0; w < 4; ++w) o[w] = pack_fp8x4(sp[(4 * w) * 33] * scale, sp[(4 * w + 1) * 33] * scale, sp[(4 * w + 2) * 33] * scale, sp[(4 * w + 3) * 33] * scale);
;         *(u32x4*)(W8 + (size_t)(n_dst + n) * pitch + kofs + k0 + ck) = o; }
	v_cvt_pk_fp8_f32 v9, v75, v79
	v_cvt_pk_fp8_f32 v10, v83, v87
	v_cvt_pk_fp8_f32 v11, v91, v95
	v_and_b32_e32 v8, 0xffff, v8
	v_and_b32_e32 v10, 0xffff, v10
	v_lshl_or_b32 v182, v9, 16, v8
	v_lshl_or_b32 v183, v11, 16, v10
	global_store_dwordx2 v173, v[182:183], s[74:75]
	s_add_u32 s47, s46, 0x800
	s_mul_hi_u32 s48, s47, 0xb60b61
	s_mul_i32 s49, s48, 0x168
	s_sub_u32 s49, s47, s49
	s_lshl_b32 s50, s48, 1
	s_or_b32 s50, s50, 1
	s_lshr_b32 s51, s49, 3
	s_and_b32 s52, s49, 7
	s_and_b32 s53, s52, 3
	s_lshr_b32 s54, s52, 2
	s_lshl_b32 s55, s53, 6
	s_lshl_b32 s56, s54, 5
	s_add_u32 s55, s55, s56
	s_bfe_u32 s56, s52, 0x10001
	s_lshl_b32 s56, s56, 7
	s_and_b32 s57, s52, 1
	s_lshl_b32 s57, s57, 5
	s_add_u32 s56, s56, s57
	s_lshl_b32 s57, s54, 6
	s_add_u32 s56, s56, s57
	s_lshl_b32 s57, s52, 5
	s_sub_u32 s58, s51, 9
	s_cmp_lt_u32 s58, 12
	s_cselect_b32 s57, s56, s57
	s_cmp_lt_u32 s51, 5
	s_cselect_b32 s57, s55, s57
	s_lshl_b32 s58, s51, 8
	s_add_u32 s57, s57, s58
	s_mul_i32 s58, s50, 0x2d0000
	s_lshl_b32 s57, s57, 2
	s_add_u32 s58, s58, s57
	s_add_u32 s60, s22, s58
	s_addc_u32 s61, s23, 0
	s_lshl_b32 s58, s49, 17
	s_lshl_b32 s59, s50, 6
	s_add_u32 s58, s58, s59
	s_add_u32 s74, s64, s58
	s_addc_u32 s75, s65, 0
	global_load_dwordx4 v[64:67], v162, s[60:61] nt
	global_load_dwordx4 v[68:71], v163, s[60:61] nt
	global_load_dwordx4 v[72:75], v164, s[60:61] nt
	global_load_dwordx4 v[76:79], v165, s[60:61] nt
	global_load_dwordx4 v[80:83], v166, s[60:61] nt
	global_load_dwordx4 v[84:87], v167, s[60:61] nt
	global_load_dwordx4 v[88:91], v168, s[60:61] nt
	global_load_dwordx4 v[92:95], v169, s[60:61] nt
	s_waitcnt vmcnt(20)
	v_pk_mul_f32 v[96:97], v[96:97], s[44:45]
	v_pk_mul_f32 v[98:99], v[98:99], s[44:45]
	v_pk_mul_f32 v[100:101], v[100:101], s[44:45]
	v_pk_mul_f32 v[102:103], v[102:103], s[44:45]
	v_pk_mul_f32 v[104:105], v[104:105], s[44:45]
	v_pk_mul_f32 v[106:107], v[106:107], s[44:45]
	v_pk_mul_f32 v[108:109], v[108:109], s[44:45]
	v_pk_mul_f32 v[110:111], v[110:111], s[44:45]
	v_pk_mul_f32 v[112:113], v[112:113], s[44:45]
	v_pk_mul_f32 v[114:115], v[114:115], s[44:45]
	v_pk_mul_f32 v[116:117], v[116:117], s[44:45]
	v_pk_mul_f32 v[118:119], v[118:119], s[44:45]
	v_pk_mul_f32 v[120:121], v[120:121], s[44:45]
	v_pk_mul_f32 v[122:123], v[122:123], s[44:45]
	v_pk_mul_f32 v[124:125], v[124:125], s[44:45]
	v_pk_mul_f32 v[126:127], v[126:127], s[44:45]
	v_cvt_pk_fp8_f32 v8, v96, v100
	v_cvt_pk_fp8_f32 v9, v104, v108
	v_cvt_pk_fp8_f32 v10, v112, v116
	v_cvt_pk_fp8_f32 v11, v120, v124
	v_and_b32_e32 v8, 0xffff, v8
	v_and_b32_e32 v10, 0xffff, v10
	v_lshl_or_b32 v184, v9, 16, v8
	v_lshl_or_b32 v185, v11, 16, v10
	global_store_dwordx2 v170, v[184:185], s[76:77]
	v_cvt_pk_fp8_f32 v8, v97, v101
	v_cvt_pk_fp8_f32 v9, v105, v109
	v_cvt_pk_fp8_f32 v10, v113, v117
	v_cvt_pk_fp8_f32 v11, v121, v125
	v_and_b32_e32 v8, 0xffff, v8
	v_and_b32_e32 v10, 0xffff, v10
	v_lshl_or_b32 v186, v9, 16, v8
	v_lshl_or_b32 v187, v11, 16, v10
	global_store_dwordx2 v171, v[186:187], s[76:77]
	v_cvt_pk_fp8_f32 v8, v98, v102
	v_cvt_pk_fp8_f32 v9, v106, v110
	v_cvt_pk_fp8_f32 v10, v114, v118
	v_cvt_pk_fp8_f32 v11, v122, v126
	v_and_b32_e32 v8, 0xffff, v8
	v_and_b32_e32 v10, 0xffff, v10
	v_lshl_or_b32 v188, v9, 16, v8
	v_lshl_or_b32 v189, v11, 16, v10
	global_store_dwordx2 v172, v[188:189], s[76:77]
	v_cvt_pk_fp8_f32 v8, v99, v103
	v_cvt_pk_fp8_f32 v9, v107, v111
	v_cvt_pk_fp8_f32 v10, v115, v119
	v_cvt_pk_fp8_f32 v11, v123, v127
	v_and_b32_e32 v8, 0xffff, v8
	v_and_b32_e32 v10, 0xffff, v10
	v_lshl_or_b32 v190, v9, 16, v8
	v_lshl_or_b32 v191, v11, 16, v10
	global_store_dwordx2 v173, v[190:191], s[76:77]
	s_add_u32 s47, s46, 0x1000
	s_mul_hi_u32 s48, s47, 0xb60b61
	s_mul_i32 s49, s48, 0x168
	s_sub_u32 s49, s47, s49
	s_lshl_b32 s50, s48, 1
	s_lshr_b32 s51, s49, 3
	s_and_b32 s52, s49, 7
	s_and_b32 s53, s52, 3
	s_lshr_b32 s54, s52, 2
	s_lshl_b32 s55, s53, 6
	s_lshl_b32 s56, s54, 5
	s_add_u32 s55, s55, s56
	s_bfe_u32 s56, s52, 0x10001
	s_lshl_b32 s56, s56, 7
	s_and_b32 s57, s52, 1
	s_lshl_b32 s57, s57, 5
	s_add_u32 s56, s56, s57
	s_lshl_b32 s57, s54, 6
	s_add_u32 s56, s56, s57
	s_lshl_b32 s57, s52, 5
	s_sub_u32 s58, s51, 9
	s_cmp_lt_u32 s58, 12
	s_cselect_b32 s57, s56, s57
	s_cmp_lt_u32 s51, 5
	s_cselect_b32 s57, s55, s57
	s_lshl_b32 s58, s51, 8
	s_add_u32 s57, s57, s58
	s_mul_i32 s58, s50, 0x2d0000
	s_lshl_b32 s57, s57, 2
	s_add_u32 s58, s58, s57
	s_add_u32 s60, s22, s58
	s_addc_u32 s61, s23, 0
	s_lshl_b32 s58, s49, 17
	s_lshl_b32 s59, s50, 6
	s_add_u32 s58, s58, s59
	s_add_u32 s76, s64, s58
	s_addc_u32 s77, s65, 0
	global_load_dwordx4 v[96:99], v162, s[60:61] nt
	global_load_dwordx4 v[100:103], v163, s[60:61] nt
	global_load_dwordx4 v[104:107], v164, s[60:61] nt
	global_load_dwordx4 v[108:111], v165, s[60:61] nt
	global_load_dwordx4 v[112:115], v166, s[60:61] nt
	global_load_dwordx4 v[116:119], v167, s[60:61] nt
	global_load_dwordx4 v[120:123], v168, s[60:61] nt
	global_load_dwordx4 v[124:127], v169, s[60:61] nt
	s_waitcnt vmcnt(24)
; #define LAS __attribute__((address_space(3)))
; __device__ __forceinline__ void transpose_item_fp8(const float* W, int N, unsigned char* W8, int pitch, int kofs, int k0, int n_src, int n_dst, float scale, LAS float* scr, int lane) {
;     const int r8 = lane >> 3, c4 = lane & 7;
;     f32x4 v[8];
; #pragma unroll
;     for (int i = 0; i < 8; ++i) v[i] = *(const f32x4*)(W + (size_t)(k0 + r8 + 8 * i) * N + n_src + 4 * c4);
; #pragma unroll
;     for (int i = 0; i < 8; ++i) { LAS float* d = scr + (r8 + 8 * i) * 33 + 4 * c4; d[0] = v[i][0]; d[1] = v[i][1]; d[2] = v[i][2]; d[3] = v[i][3]; }
;     asm volatile("s_waitcnt lgkmcnt(0)" ::: "memory");
;     const int n = lane & 31, cp = lane >> 5;
; #pragma unroll
;     for (int q = 0; q < 2; ++q) { const int ck = (2 * cp + q) * 16; const LAS float* sp = scr + ck * 33 + n; u32x4 o;
; #pragma unroll
;         for (int w = 0; w < 4; ++w) o[w] = pack_fp8x4(sp[(4 * w) * 33] * scale, sp[(4 * w + 1) * 33] * scale, sp[(4 * w + 2) * 33] * scale, sp[(4 * w + 3) * 33] * scale);
;         *(u32x4*)(W8 + (size_t)(n_dst + n) * pitch + kofs + k0 + ck) = o; }
	v_pk_mul_f32 v[128:129], v[128:129], s[44:45]
	v_pk_mul_f32 v[130:131], v[130:131], s[44:45]
	v_pk_mul_f32 v[132:133], v[132:133], s[44:45]
	v_pk_mul_f32 v[134:135], v[134:135], s[44:45]
	v_pk_mul_f32 v[136:137], v[136:137], s[44:45]
	v_pk_mul_f32 v[138:139], v[138:139], s[44:45]
	v_pk_mul_f32 v[140:141], v[140:141], s[44:45]
	v_pk_mul_f32 v[142:143], v[142:143], s[44:45]
	v_pk_mul_f32 v[144:145], v[144:145], s[44:45]
	v_pk_mul_f32 v[146:147], v[146:147], s[44:45]
	v_pk_mul_f32 v[148:149], v[148:149], s[44:45]
	v_pk_mul_f32 v[150:151], v[150:151], s[44:45]
	v_pk_mul_f32 v[152:153], v[152:153], s[44:45]
	v_pk_mul_f32 v[154:155], v[154:155], s[44:45]
	v_pk_mul_f32 v[156:157], v[156:157], s[44:45]
	v_pk_mul_f32 v[158:159], v[158:159], s[44:45]
	v_cvt_pk_fp8_f32 v8, v128, v132
	v_cvt_pk_fp8_f32 v9, v136, v140
	v_cvt_pk_fp8_f32 v10, v144, v148
	v_cvt_pk_fp8_f32 v11, v152, v156
	v_and_b32_e32 v8, 0xffff, v8
	v_and_b32_e32 v10, 0xffff, v10
	v_lshl_or_b32 v176, v9, 16, v8
	v_lshl_or_b32 v177, v11, 16, v10
	global_store_dwordx2 v170, v[176:177], s[78:79]
	v_cvt_pk_fp8_f32 v8, v129, v133
	v_cvt_pk_fp8_f32 v9, v137, v141
	v_cvt_pk_fp8_f32 v10, v145, v149
	v_cvt_pk_fp8_f32 v11, v153, v157
	v_and_b32_e32 v8, 0xffff, v8
	v_and_b32_e32 v10, 0xffff, v10
	v_lshl_or_b32 v178, v9, 16, v8
	v_lshl_or_b32 v179, v11, 16, v10
	global_store_dwordx2 v171, v[178:179], s[78:79]
	v_cvt_pk_fp8_f32 v8, v130, v134
	v_cvt_pk_fp8_f32 v9, v138, v142
	v_cvt_pk_fp8_f32 v10, v146, v150
	v_cvt_pk_fp8_f32 v11, v154, v158
	v_and_b32_e32 v8, 0xffff, v8
	v_and_b32_e32 v10, 0xffff, v10
	v_lshl_or_b32 v180, v9, 16, v8
	v_lshl_or_b32 v181, v11, 16, v10
	global_store_dwordx2 v172, v[180:181], s[78:79]
	v_cvt_pk_fp8_f32 v8, v131, v135
	v_cvt_pk_fp8_f32 v9, v139, v143
	v_cvt_pk_fp8_f32 v10, v147, v151
	v_cvt_pk_fp8_f32 v11, v155, v159
	v_and_b32_e32 v8, 0xffff, v8
	v_and_b32_e32 v10, 0xffff, v10
	v_lshl_or_b32 v182, v9, 16, v8
	v_lshl_or_b32 v183, v11, 16, v10
	global_store_dwordx2 v173, v[182:183], s[78:79]
	s_add_u32 s47, s46, 0x1000
	s_mul_hi_u32 s48, s47, 0xb60b61
	s_mul_i32 s49, s48, 0x168
	s_sub_u32 s49, s47, s49
	s_lshl_b32 s50, s48, 1
	s_or_b32 s50, s50, 1
	s_lshr_b32 s51, s49, 3
	s_and_b32 s52, s49, 7
	s_and_b32 s53, s52, 3
	s_lshr_b32 s54, s52, 2
	s_lshl_b32 s55, s53, 6
	s_lshl_b32 s56, s54, 5
	s_add_u32 s55, s55, s56
	s_bfe_u32 s56, s52, 0x10001
	s_lshl_b32 s56, s56, 7
	s_and_b32 s57, s52, 1
	s_lshl_b32 s57, s57, 5
	s_add_u32 s56, s56, s57
	s_lshl_b32 s57, s54, 6
	s_add_u32 s56, s56, s57
	s_lshl_b32 s57, s52, 5
	s_sub_u32 s58, s51, 9
	s_cmp_lt_u32 s58, 12
	s_cselect_b32 s57, s56, s57
	s_cmp_lt_u32 s51, 5
	s_cselect_b32 s57, s55, s57
	s_lshl_b32 s58, s51, 8
	s_add_u32 s57, s57, s58
	s_mul_i32 s58, s50, 0x2d0000
	s_lshl_b32 s57, s57, 2
	s_add_u32 s58, s58, s57
	s_add_u32 s60, s22, s58
	s_addc_u32 s61, s23, 0
	s_lshl_b32 s58, s49, 17
	s_lshl_b32 s59, s50, 6
	s_add_u32 s58, s58, s59
	s_add_u32 s78, s64, s58
	s_addc_u32 s79, s65, 0
	global_load_dwordx4 v[128:131], v162, s[60:61] nt
	global_load_dwordx4 v[132:135], v163, s[60:61] nt
	global_load_dwordx4 v[136:139], v164, s[60:61] nt
	global_load_dwordx4 v[140:143], v165, s[60:61] nt
	global_load_dwordx4 v[144:147], v166, s[60:61] nt
	global_load_dwordx4 v[148:151], v167, s[60:61] nt
	global_load_dwordx4 v[152:155], v168, s[60:61] nt
	global_load_dwordx4 v[156:159], v169, s[60:61] nt
	s_waitcnt vmcnt(24)
	v_pk_mul_f32 v[64:65], v[64:65], s[44:45]
	v_pk_mul_f32 v[66:67], v[66:67], s[44:45]
	v_pk_mul_f32 v[68:69], v[68:69], s[44:45]
	v_pk_mul_f32 v[70:71], v[70:71], s[44:45]
	v_pk_mul_f32 v[72:73], v[72:73], s[44:45]
	v_pk_mul_f32 v[74:75], v[74:75], s[44:45]
	v_pk_mul_f32 v[76:77], v[76:77], s[44:45]
	v_pk_mul_f32 v[78:79], v[78:79], s[44:45]
	v_pk_mul_f32 v[80:81], v[80:81], s[44:45]
	v_pk_mul_f32 v[82:83], v[82:83], s[44:45]
	v_pk_mul_f32 v[84:85], v[84:85], s[44:45]
	v_pk_mul_f32 v[86:87], v[86:87], s[44:45]
	v_pk_mul_f32 v[88:89], v[88:89], s[44:45]
	v_pk_mul_f32 v[90:91], v[90:91], s[44:45]
	v_pk_mul_f32 v[92:93], v[92:93], s[44:45]
	v_pk_mul_f32 v[94:95], v[94:95], s[44:45]
	v_cvt_pk_fp8_f32 v8, v64, v68
	v_cvt_pk_fp8_f32 v9, v72, v76
	v_cvt_pk_fp8_f32 v10, v80, v84
	v_cvt_pk_fp8_f32 v11, v88, v92
	v_and_b32_e32 v8, 0xffff, v8
	v_and_b32_e32 v10, 0xffff, v10
	v_lshl_or_b32 v184, v9, 16, v8
	v_lshl_or_b32 v185, v11, 16, v10
	global_store_dwordx2 v170, v[184:185], s[74:75]
	v_cvt_pk_fp8_f32 v8, v65, v69
	v_cvt_pk_fp8_f32 v9, v73, v77
	v_cvt_pk_fp8_f32 v10, v81, v85
	v_cvt_pk_fp8_f32 v11, v89, v93
	v_and_b32_e32 v8, 0xffff, v8
	v_and_b32_e32 v10, 0xffff, v10
	v_lshl_or_b32 v186, v9, 16, v8
	v_lshl_or_b32 v187, v11, 16, v10
	global_store_dwordx2 v171, v[186:187], s[74:75]
	v_cvt_pk_fp8_f32 v8, v66, v70
	v_cvt_pk_fp8_f32 v9, v74, v78
	v_cvt_pk_fp8_f32 v10, v82, v86
	v_cvt_pk_fp8_f32 v11, v90, v94
	v_and_b32_e32 v8, 0xffff, v8
	v_and_b32_e32 v10, 0xffff, v10
	v_lshl_or_b32 v188, v9, 16, v8
	v_lshl_or_b32 v189, v11, 16, v10
	global_store_dwordx2 v172, v[188:189], s[74:75]
	v_cvt_pk_fp8_f32 v8, v67, v71
	v_cvt_pk_fp8_f32 v9, v75, v79
	v_cvt_pk_fp8_f32 v10, v83, v87
	v_cvt_pk_fp8_f32 v11, v91, v95
	v_and_b32_e32 v8, 0xffff, v8
	v_and_b32_e32 v10, 0xffff, v10
	v_lshl_or_b32 v190, v9, 16, v8
	v_lshl_or_b32 v191, v11, 16, v10
	global_store_dwordx2 v173, v[190:191], s[74:75]
	s_waitcnt vmcnt(16)
; #define LAS __attribute__((address_space(3)))
; __host__ __device__ __forceinline__ int tile_mode(int pn) { return (pn <= 4) ? 1 : (pn >= 9 && pn <= 20) ? 2 : 0; }
; __host__ __device__ __forceinline__ int gemm_col_to_orig(int nprime) {
;     const int pn = nprime >> 8, xp = nprime & 255, bj = xp >> 7, x = xp & 127, md = tile_mode(pn);
;     if (md == 1) return 256 * pn + 64 * (x >> 5) + (x & 31) + 32 * bj;
;     if (md == 2) return 256 * pn + 128 * (x >> 6) + (x & 63) + 64 * bj;
;     return nprime;
; }
; __device__ __forceinline__ void transpose_item_fp8(const float* W, int N, unsigned char* W8, int pitch, int kofs, int k0, int n_src, int n_dst, float scale, LAS float* scr, int lane) {
;     const int r8 = lane >> 3, c4 = lane & 7;
;     f32x4 v[8];
; #pragma unroll
;     for (int i = 0; i < 8; ++i) v[i] = *(const f32x4*)(W + (size_t)(k0 + r8 + 8 * i) * N + n_src + 4 * c4);
; #pragma unroll
;     for (int i = 0; i < 8; ++i) { LAS float* d = scr + (r8 + 8 * i) * 33 + 4 * c4; d[0] = v[i][0]; d[1] = v[i][1]; d[2] = v[i][2]; d[3] = v[i][3]; }
;     asm volatile("s_waitcnt lgkmcnt(0)" ::: "memory");
;     const int n = lane & 31, cp = lane >> 5;
; #pragma unroll
;     for (int q = 0; q < 2; ++q) { const int ck = (2 * cp + q) * 16; const LAS float* sp = scr + ck * 33 + n; u32x4 o;
; #pragma unroll
;         for (int w = 0; w < 4; ++w) o[w] = pack_fp8x4(sp[(4 * w) * 33] * scale, sp[(4 * w + 1) * 33] * scale, sp[(4 * w + 2) * 33] * scale, sp[(4 * w + 3) * 33] * scale);
;         *(u32x4*)(W8 + (size_t)(n_dst + n) * pitch + kofs + k0 + ck) = o; }
	v_pk_mul_f32 v[96:97], v[96:97], s[44:45]
	v_pk_mul_f32 v[98:99], v[98:99], s[44:45]
	v_pk_mul_f32 v[100:101], v[100:101], s[44:45]
	v_pk_mul_f32 v[102:103], v[102:103], s[44:45]
	v_pk_mul_f32 v[104:105], v[104:105], s[44:45]
	v_pk_mul_f32 v[106:107], v[106:107], s[44:45]
	v_pk_mul_f32 v[108:109], v[108:109], s[44:45]
	v_pk_mul_f32 v[110:111], v[110:111], s[44:45]
	v_pk_mul_f32 v[112:113], v[112:113], s[44:45]
	v_pk_mul_f32 v[114:115], v[114:115], s[44:45]
	v_pk_mul_f32 v[116:117], v[116:117], s[44:45]
	v_pk_mul_f32 v[118:119], v[118:119], s[44:45]
	v_pk_mul_f32 v[120:121], v[120:121], s[44:45]
	v_pk_mul_f32 v[122:123], v[122:123], s[44:45]
	v_pk_mul_f32 v[124:125], v[124:125], s[44:45]
	v_pk_mul_f32 v[126:127], v[126:127], s[44:45]
	v_cvt_pk_fp8_f32 v8, v96, v100
	v_cvt_pk_fp8_f32 v9, v104, v108
	v_cvt_pk_fp8_f32 v10, v112, v116
	v_cvt_pk_fp8_f32 v11, v120, v124
	v_and_b32_e32 v8, 0xffff, v8
	v_and_b32_e32 v10, 0xffff, v10
	v_lshl_or_b32 v176, v9, 16, v8
	v_lshl_or_b32 v177, v11, 16, v10
	global_store_dwordx2 v170, v[176:177], s[76:77]
	v_cvt_pk_fp8_f32 v8, v97, v101
	v_cvt_pk_fp8_f32 v9, v105, v109
	v_cvt_pk_fp8_f32 v10, v113, v117
	v_cvt_pk_fp8_f32 v11, v121, v125
	v_and_b32_e32 v8, 0xffff, v8
	v_and_b32_e32 v10, 0xffff, v10
	v_lshl_or_b32 v178, v9, 16, v8
	v_lshl_or_b32 v179, v11, 16, v10
	global_store_dwordx2 v171, v[178:179], s[76:77]
	v_cvt_pk_fp8_f32 v8, v98, v102
	v_cvt_pk_fp8_f32 v9, v106, v110
	v_cvt_pk_fp8_f32 v10, v114, v118
	v_cvt_pk_fp8_f32 v11, v122, v126
	v_and_b32_e32 v8, 0xffff, v8
	v_and_b32_e32 v10, 0xffff, v10
	v_lshl_or_b32 v180, v9, 16, v8
	v_lshl_or_b32 v181, v11, 16, v10
	global_store_dwordx2 v172, v[180:181], s[76:77]
	v_cvt_pk_fp8_f32 v8, v99, v103
	v_cvt_pk_fp8_f32 v9, v107, v111
	v_cvt_pk_fp8_f32 v10, v115, v119
	v_cvt_pk_fp8_f32 v11, v123, v127
	v_and_b32_e32 v8, 0xffff, v8
	v_and_b32_e32 v10, 0xffff, v10
	v_lshl_or_b32 v182, v9, 16, v8
	v_lshl_or_b32 v183, v11, 16, v10
	global_store_dwordx2 v173, v[182:183], s[76:77]
	s_waitcnt vmcnt(8)
	v_pk_mul_f32 v[128:129], v[128:129], s[44:45]
	v_pk_mul_f32 v[130:131], v[130:131], s[44:45]
	v_pk_mul_f32 v[132:133], v[132:133], s[44:45]
	v_pk_mul_f32 v[134:135], v[134:135], s[44:45]
	v_pk_mul_f32 v[136:137], v[136:137], s[44:45]
	v_pk_mul_f32 v[138:139], v[138:139], s[44:45]
	v_pk_mul_f32 v[140:141], v[140:141], s[44:45]
	v_pk_mul_f32 v[142:143], v[142:143], s[44:45]
	v_pk_mul_f32 v[144:145], v[144:145], s[44:45]
	v_pk_mul_f32 v[146:147], v[146:147], s[44:45]
	v_pk_mul_f32 v[148:149], v[148:149], s[44:45]
	v_pk_mul_f32 v[150:151], v[150:151], s[44:45]
	v_pk_mul_f32 v[152:153], v[152:153], s[44:45]
	v_pk_mul_f32 v[154:155], v[154:155], s[44:45]
	v_pk_mul_f32 v[156:157], v[156:157], s[44:45]
	v_pk_mul_f32 v[158:159], v[158:159], s[44:45]
	v_cvt_pk_fp8_f32 v8, v128, v132
	v_cvt_pk_fp8_f32 v9, v136, v140
	v_cvt_pk_fp8_f32 v10, v144, v148
	v_cvt_pk_fp8_f32 v11, v152, v156
	v_and_b32_e32 v8, 0xffff, v8
	v_and_b32_e32 v10, 0xffff, v10
	v_lshl_or_b32 v184, v9, 16, v8
	v_lshl_or_b32 v185, v11, 16, v10
	global_store_dwordx2 v170, v[184:185], s[78:79]
	v_cvt_pk_fp8_f32 v8, v129, v133
	v_cvt_pk_fp8_f32 v9, v137, v141
	v_cvt_pk_fp8_f32 v10, v145, v149
	v_cvt_pk_fp8_f32 v11, v153, v157
	v_and_b32_e32 v8, 0xffff, v8
	v_and_b32_e32 v10, 0xffff, v10
	v_lshl_or_b32 v186, v9, 16, v8
	v_lshl_or_b32 v187, v11, 16, v10
	global_store_dwordx2 v171, v[186:187], s[78:79]
	v_cvt_pk_fp8_f32 v8, v130, v134
	v_cvt_pk_fp8_f32 v9, v138, v142
	v_cvt_pk_fp8_f32 v10, v146, v150
	v_cvt_pk_fp8_f32 v11, v154, v158
	v_and_b32_e32 v8, 0xffff, v8
	v_and_b32_e32 v10, 0xffff, v10
	v_lshl_or_b32 v188, v9, 16, v8
	v_lshl_or_b32 v189, v11, 16, v10
	global_store_dwordx2 v172, v[188:189], s[78:79]
	v_cvt_pk_fp8_f32 v8, v131, v135
	v_cvt_pk_fp8_f32 v9, v139, v143
	v_cvt_pk_fp8_f32 v10, v147, v151
	v_cvt_pk_fp8_f32 v11, v155, v159
	v_and_b32_e32 v8, 0xffff, v8
	v_and_b32_e32 v10, 0xffff, v10
	v_lshl_or_b32 v190, v9, 16, v8
	v_lshl_or_b32 v191, v11, 16, v10
	global_store_dwordx2 v173, v[190:191], s[78:79]
	s_branch .Lp0c_end
.Lp0c_four:
	s_add_u32 s47, s46, 0x0
	s_mul_hi_u32 s48, s47, 0xb60b61
	s_mul_i32 s49, s48, 0x168
	s_sub_u32 s49, s47, s49
	s_lshl_b32 s50, s48, 1
	s_lshr_b32 s51, s49, 3
	s_and_b32 s52, s49, 7
	s_and_b32 s53, s52, 3
	s_lshr_b32 s54, s52, 2
	s_lshl_b32 s55, s53, 6
	s_lshl_b32 s56, s54, 5
	s_add_u32 s55, s55, s56
	s_bfe_u32 s56, s52, 0x10001
	s_lshl_b32 s56, s56, 7
	s_and_b32 s57, s52, 1
	s_lshl_b32 s57, s57, 5
	s_add_u32 s56, s56, s57
	s_lshl_b32 s57, s54, 6
	s_add_u32 s56, s56, s57
	s_lshl_b32 s57, s52, 5
	s_sub_u32 s58, s51, 9
	s_cmp_lt_u32 s58, 12
	s_cselect_b32 s57, s56, s57
	s_cmp_lt_u32 s51, 5
	s_cselect_b32 s57, s55, s57
	s_lshl_b32 s58, s51, 8
	s_add_u32 s57, s57, s58
	s_mul_i32 s58, s50, 0x2d0000
	s_lshl_b32 s57, s57, 2
	s_add_u32 s58, s58, s57
	s_add_u32 s60, s22, s58
	s_addc_u32 s61, s23, 0
	s_lshl_b32 s58, s49, 17
	s_lshl_b32 s59, s50, 6
	s_add_u32 s58, s58, s59
	s_add_u32 s74, s64, s58
	s_addc_u32 s75, s65, 0
	global_load_dwordx4 v[64:67], v162, s[60:61] nt
	global_load_dwordx4 v[68:71], v163, s[60:61] nt
	global_load_dwordx4 v[72:75], v164, s[60:61] nt
	global_load_dwordx4 v[76:79], v165, s[60:61] nt
	global_load_dwordx4 v[80:83], v166, s[60:61] nt
	global_load_dwordx4 v[84:87], v167, s[60:61] nt
	global_load_dwordx4 v[88:91], v168, s[60:61] nt
	global_load_dwordx4 v[92:95], v169, s[60:61] nt
	s_add_u32 s47, s46, 0x0
	s_mul_hi_u32 s48, s47, 0xb60b61
	s_mul_i32 s49, s48, 0x168
	s_sub_u32 s49, s47, s49
	s_lshl_b32 s50, s48, 1
	s_or_b32 s50, s50, 1
	s_lshr_b32 s51, s49, 3
	s_and_b32 s52, s49, 7
	s_and_b32 s53, s52, 3
	s_lshr_b32 s54, s52, 2
	s_lshl_b32 s55, s53, 6
	s_lshl_b32 s56, s54, 5
; #define LAS __attribute__((address_space(3)))
; __host__ __device__ __forceinline__ int tile_mode(int pn) { return (pn <= 4) ? 1 : (pn >= 9 && pn <= 20) ? 2 : 0; }
; __host__ __device__ __forceinline__ int gemm_col_to_orig(int nprime) {
;     const int pn = nprime >> 8, xp = nprime & 255, bj = xp >> 7, x = xp & 127, md = tile_mode(pn);
;     if (md == 1) return 256 * pn + 64 * (x >> 5) + (x & 31) + 32 * bj;
;     if (md == 2) return 256 * pn + 128 * (x >> 6) + (x & 63) + 64 * bj;
;     return nprime;
; }
; __device__ __forceinline__ void transpose_item_fp8(const float* W, int N, unsigned char* W8, int pitch, int kofs, int k0, int n_src, int n_dst, float scale, LAS float* scr, int lane) {
;     const int r8 = lane >> 3, c4 = lane & 7;
;     f32x4 v[8];
; #pragma unroll
;     for (int i = 0; i < 8; ++i) v[i] = *(const f32x4*)(W + (size_t)(k0 + r8 + 8 * i) * N + n_src + 4 * c4);
; #pragma unroll
;     for (int i = 0; i < 8; ++i) { LAS float* d = scr + (r8 + 8 * i) * 33 + 4 * c4; d[0] = v[i][0]; d[1] = v[i][1]; d[2] = v[i][2]; d[3] = v[i][3]; }
;     asm volatile("s_waitcnt lgkmcnt(0)" ::: "memory");
;     const int n = lane & 31, cp = lane >> 5;
; #pragma unroll
;     for (int q = 0; q < 2; ++q) { const int ck = (2 * cp + q) * 16; const LAS float* sp = scr + ck * 33 + n; u32x4 o;
; #pragma unroll
;         for (int w = 0; w < 4; ++w) o[w] = pack_fp8x4(sp[(4 * w) * 33] * scale, sp[(4 * w + 1) * 33] * scale, sp[(4 * w + 2) * 33] * scale, sp[(4 * w + 3) * 33] * scale);
;         *(u32x4*)(W8 + (size_t)(n_dst + n) * pitch + kofs + k0 + ck) = o; }
	s_add_u32 s55, s55, s56
	s_bfe_u32 s56, s52, 0x10001
	s_lshl_b32 s56, s56, 7
	s_and_b32 s57, s52, 1
	s_lshl_b32 s57, s57, 5
	s_add_u32 s56, s56, s57
	s_lshl_b32 s57, s54, 6
	s_add_u32 s56, s56, s57
	s_lshl_b32 s57, s52, 5
	s_sub_u32 s58, s51, 9
	s_cmp_lt_u32 s58, 12
	s_cselect_b32 s57, s56, s57
	s_cmp_lt_u32 s51, 5
	s_cselect_b32 s57, s55, s57
	s_lshl_b32 s58, s51, 8
	s_add_u32 s57, s57, s58
	s_mul_i32 s58, s50, 0x2d0000
	s_lshl_b32 s57, s57, 2
	s_add_u32 s58, s58, s57
	s_add_u32 s60, s22, s58
	s_addc_u32 s61, s23, 0
	s_lshl_b32 s58, s49, 17
	s_lshl_b32 s59, s50, 6
	s_add_u32 s58, s58, s59
	s_add_u32 s76, s64, s58
	s_addc_u32 s77, s65, 0
	global_load_dwordx4 v[96:99], v162, s[60:61] nt
	global_load_dwordx4 v[100:103], v163, s[60:61] nt
	global_load_dwordx4 v[104:107], v164, s[60:61] nt
	global_load_dwordx4 v[108:111], v165, s[60:61] nt
	global_load_dwordx4 v[112:115], v166, s[60:61] nt
	global_load_dwordx4 v[116:119], v167, s[60:61] nt
	global_load_dwordx4 v[120:123], v168, s[60:61] nt
	global_load_dwordx4 v[124:127], v169, s[60:61] nt
	s_add_u32 s47, s46, 0x800
	s_mul_hi_u32 s48, s47, 0xb60b61
	s_mul_i32 s49, s48, 0x168
	s_sub_u32 s49, s47, s49
	s_lshl_b32 s50, s48, 1
	s_lshr_b32 s51, s49, 3
	s_and_b32 s52, s49, 7
	s_and_b32 s53, s52, 3
	s_lshr_b32 s54, s52, 2
	s_lshl_b32 s55, s53, 6
	s_lshl_b32 s56, s54, 5
	s_add_u32 s55, s55, s56
	s_bfe_u32 s56, s52, 0x10001
	s_lshl_b32 s56, s56, 7
	s_and_b32 s57, s52, 1
	s_lshl_b32 s57, s57, 5
	s_add_u32 s56, s56, s57
	s_lshl_b32 s57, s54, 6
	s_add_u32 s56, s56, s57
	s_lshl_b32 s57, s52, 5
	s_sub_u32 s58, s51, 9
	s_cmp_lt_u32 s58, 12
	s_cselect_b32 s57, s56, s57
	s_cmp_lt_u32 s51, 5
	s_cselect_b32 s57, s55, s57
	s_lshl_b32 s58, s51, 8
	s_add_u32 s57, s57, s58
	s_mul_i32 s58, s50, 0x2d0000
	s_lshl_b32 s57, s57, 2
	s_add_u32 s58, s58, s57
	s_add_u32 s60, s22, s58
	s_addc_u32 s61, s23, 0
	s_lshl_b32 s58, s49, 17
	s_lshl_b32 s59, s50, 6
	s_add_u32 s58, s58, s59
	s_add_u32 s78, s64, s58
	s_addc_u32 s79, s65, 0
	global_load_dwordx4 v[128:131], v162, s[60:61] nt
	global_load_dwordx4 v[132:135], v163, s[60:61] nt
	global_load_dwordx4 v[136:139], v164, s[60:61] nt
	global_load_dwordx4 v[140:143], v165, s[60:61] nt
	global_load_dwordx4 v[144:147], v166, s[60:61] nt
	global_load_dwordx4 v[148:151], v167, s[60:61] nt
	global_load_dwordx4 v[152:155], v168, s[60:61] nt
	global_load_dwordx4 v[156:159], v169, s[60:61] nt
	s_waitcnt vmcnt(16)
	v_pk_mul_f32 v[64:65], v[64:65], s[44:45]
	v_pk_mul_f32 v[66:67], v[66:67], s[44:45]
	v_pk_mul_f32 v[68:69], v[68:69], s[44:45]
	v_pk_mul_f32 v[70:71], v[70:71], s[44:45]
	v_pk_mul_f32 v[72:73], v[72:73], s[44:45]
	v_pk_mul_f32 v[74:75], v[74:75], s[44:45]
	v_pk_mul_f32 v[76:77], v[76:77], s[44:45]
	v_pk_mul_f32 v[78:79], v[78:79], s[44:45]
	v_pk_mul_f32 v[80:81], v[80:81], s[44:45]
	v_pk_mul_f32 v[82:83], v[82:83], s[44:45]
	v_pk_mul_f32 v[84:85], v[84:85], s[44:45]
	v_pk_mul_f32 v[86:87], v[86:87], s[44:45]
	v_pk_mul_f32 v[88:89], v[88:89], s[44:45]
	v_pk_mul_f32 v[90:91], v[90:91], s[44:45]
	v_pk_mul_f32 v[92:93], v[92:93], s[44:45]
	v_pk_mul_f32 v[94:95], v[94:95], s[44:45]
	v_cvt_pk_fp8_f32 v8, v64, v68
	v_cvt_pk_fp8_f32 v9, v72, v76
	v_cvt_pk_fp8_f32 v10, v80, v84
	v_cvt_pk_fp8_f32 v11, v88, v92
	v_and_b32_e32 v8, 0xffff, v8
	v_and_b32_e32 v10, 0xffff, v10
	v_lshl_or_b32 v176, v9, 16, v8
	v_lshl_or_b32 v177, v11, 16, v10
	global_store_dwordx2 v170, v[176:177], s[74:75]
	v_cvt_pk_fp8_f32 v8, v65, v69
	v_cvt_pk_fp8_f32 v9, v73, v77
	v_cvt_pk_fp8_f32 v10, v81, v85
	v_cvt_pk_fp8_f32 v11, v89, v93
	v_and_b32_e32 v8, 0xffff, v8
	v_and_b32_e32 v10, 0xffff, v10
	v_lshl_or_b32 v178, v9, 16, v8
	v_lshl_or_b32 v179, v11, 16, v10
	global_store_dwordx2 v171, v[178:179], s[74:75]
	v_cvt_pk_fp8_f32 v8, v66, v70
	v_cvt_pk_fp8_f32 v9, v74, v78
	v_cvt_pk_fp8_f32 v10, v82, v86
	v_cvt_pk_fp8_f32 v11, v90, v94
	v_and_b32_e32 v8, 0xffff, v8
	v_and_b32_e32 v10, 0xffff, v10
	v_lshl_or_b32 v180, v9, 16, v8
	v_lshl_or_b32 v181, v11, 16, v10
	global_store_dwordx2 v172, v[180:181], s[74:75]
	v_cvt_pk_fp8_f32 v8, v67, v71
	v_cvt_pk_fp8_f32 v9, v75, v79
	v_cvt_pk_fp8_f32 v10, v83, v87
	v_cvt_pk_fp8_f32 v11, v91, v95
	v_and_b32_e32 v8, 0xffff, v8
	v_and_b32_e32 v10, 0xffff, v10
	v_lshl_or_b32 v182, v9, 16, v8
	v_lshl_or_b32 v183, v11, 16, v10
	global_store_dwordx2 v173, v[182:183], s[74:75]
	s_add_u32 s47, s46, 0x800
	s_mul_hi_u32 s48, s47, 0xb60b61
	s_mul_i32 s49, s48, 0x168
	s_sub_u32 s49, s47, s49
	s_lshl_b32 s50, s48, 1
	s_or_b32 s50, s50, 1
	s_lshr_b32 s51, s49, 3
	s_and_b32 s52, s49, 7
	s_and_b32 s53, s52, 3
	s_lshr_b32 s54, s52, 2
	s_lshl_b32 s55, s53, 6
	s_lshl_b32 s56, s54, 5
	s_add_u32 s55, s55, s56
	s_bfe_u32 s56, s52, 0x10001
	s_lshl_b32 s56, s56, 7
	s_and_b32 s57, s52, 1
	s_lshl_b32 s57, s57, 5
	s_add_u32 s56, s56, s57
	s_lshl_b32 s57, s54, 6
	s_add_u32 s56, s56, s57
	s_lshl_b32 s57, s52, 5
	s_sub_u32 s58, s51, 9
	s_cmp_lt_u32 s58, 12
	s_cselect_b32 s57, s56, s57
	s_cmp_lt_u32 s51, 5
	s_cselect_b32 s57, s55, s57
	s_lshl_b32 s58, s51, 8
	s_add_u32 s57, s57, s58
	s_mul_i32 s58, s50, 0x2d0000
	s_lshl_b32 s57, s57, 2
	s_add_u32 s58, s58, s57
	s_add_u32 s60, s22, s58
	s_addc_u32 s61, s23, 0
	s_lshl_b32 s58, s49, 17
	s_lshl_b32 s59, s50, 6
	s_add_u32 s58, s58, s59
	s_add_u32 s74, s64, s58
	s_addc_u32 s75, s65, 0
	global_load_dwordx4 v[64:67], v162, s[60:61] nt
	global_load_dwordx4 v[68:71], v163, s[60:61] nt
	global_load_dwordx4 v[72:75], v164, s[60:61] nt
	global_load_dwordx4 v[76:79], v165, s[60:61] nt
	global_load_dwordx4 v[80:83], v166, s[60:61] nt
	global_load_dwordx4 v[84:87], v167, s[60:61] nt
	global_load_dwordx4 v[88:91], v168, s[60:61] nt
	global_load_dwordx4 v[92:95], v169, s[60:61] nt
	s_waitcnt vmcnt(20)
; #define LAS __attribute__((address_space(3)))
; __device__ __forceinline__ void transpose_item_fp8(const float* W, int N, unsigned char* W8, int pitch, int kofs, int k0, int n_src, int n_dst, float scale, LAS float* scr, int lane) {
;     const int r8 = lane >> 3, c4 = lane & 7;
;     f32x4 v[8];
; #pragma unroll
;     for (int i = 0; i < 8; ++i) v[i] = *(const f32x4*)(W + (size_t)(k0 + r8 + 8 * i) * N + n_src + 4 * c4);
; #pragma unroll
;     for (int i = 0; i < 8; ++i) { LAS float* d = scr + (r8 + 8 * i) * 33 + 4 * c4; d[0] = v[i][0]; d[1] = v[i][1]; d[2] = v[i][2]; d[3] = v[i][3]; }
;     asm volatile("s_waitcnt lgkmcnt(0)" ::: "memory");
;     const int n = lane & 31, cp = lane >> 5;
; #pragma unroll
;     for (int q = 0; q < 2; ++q) { const int ck = (2 * cp + q) * 16; const LAS float* sp = scr + ck * 33 + n; u32x4 o;
; #pragma unroll
;         for (int w = 0; w < 4; ++w) o[w] = pack_fp8x4(sp[(4 * w) * 33] * scale, sp[(4 * w + 1) * 33] * scale, sp[(4 * w + 2) * 33] * scale, sp[(4 * w + 3) * 33] * scale);
;         *(u32x4*)(W8 + (size_t)(n_dst + n) * pitch + kofs + k0 + ck) = o; }
;     asm volatile("s_waitcnt lgkmcnt(0)" ::: "memory");
; }
; __global__ void __launch_bounds__(512, 2) hybrid_fwd(Args a) {
;     ...
;         for (int it = gw; it < I_IN; it += NGW) { const int nb = it % (DIN / 32), kb = it / (DIN / 32);
;             if ((a.fp8mask >> (nb >> 3)) & 1ull) transpose_item_fp8(a.w_in, DIN, (unsigned char*)WinT, 4096, 0, 64 * kb, gemm_col_to_orig(32 * nb), 32 * nb, W8_SCALE, scr, lane);
	v_pk_mul_f32 v[96:97], v[96:97], s[44:45]
	v_pk_mul_f32 v[98:99], v[98:99], s[44:45]
	v_pk_mul_f32 v[100:101], v[100:101], s[44:45]
	v_pk_mul_f32 v[102:103], v[102:103], s[44:45]
	v_pk_mul_f32 v[104:105], v[104:105], s[44:45]
	v_pk_mul_f32 v[106:107], v[106:107], s[44:45]
	v_pk_mul_f32 v[108:109], v[108:109], s[44:45]
	v_pk_mul_f32 v[110:111], v[110:111], s[44:45]
	v_pk_mul_f32 v[112:113], v[112:113], s[44:45]
	v_pk_mul_f32 v[114:115], v[114:115], s[44:45]
	v_pk_mul_f32 v[116:117], v[116:117], s[44:45]
	v_pk_mul_f32 v[118:119], v[118:119], s[44:45]
	v_pk_mul_f32 v[120:121], v[120:121], s[44:45]
	v_pk_mul_f32 v[122:123], v[122:123], s[44:45]
	v_pk_mul_f32 v[124:125], v[124:125], s[44:45]
	v_pk_mul_f32 v[126:127], v[126:127], s[44:45]
	v_cvt_pk_fp8_f32 v8, v96, v100
	v_cvt_pk_fp8_f32 v9, v104, v108
	v_cvt_pk_fp8_f32 v10, v112, v116
	v_cvt_pk_fp8_f32 v11, v120, v124
	v_and_b32_e32 v8, 0xffff, v8
	v_and_b32_e32 v10, 0xffff, v10
	v_lshl_or_b32 v184, v9, 16, v8
	v_lshl_or_b32 v185, v11, 16, v10
	global_store_dwordx2 v170, v[184:185], s[76:77]
	v_cvt_pk_fp8_f32 v8, v97, v101
	v_cvt_pk_fp8_f32 v9, v105, v109
	v_cvt_pk_fp8_f32 v10, v113, v117
	v_cvt_pk_fp8_f32 v11, v121, v125
	v_and_b32_e32 v8, 0xffff, v8
	v_and_b32_e32 v10, 0xffff, v10
	v_lshl_or_b32 v186, v9, 16, v8
	v_lshl_or_b32 v187, v11, 16, v10
	global_store_dwordx2 v171, v[186:187], s[76:77]
	v_cvt_pk_fp8_f32 v8, v98, v102
	v_cvt_pk_fp8_f32 v9, v106, v110
	v_cvt_pk_fp8_f32 v10, v114, v118
	v_cvt_pk_fp8_f32 v11, v122, v126
	v_and_b32_e32 v8, 0xffff, v8
	v_and_b32_e32 v10, 0xffff, v10
	v_lshl_or_b32 v188, v9, 16, v8
	v_lshl_or_b32 v189, v11, 16, v10
	global_store_dwordx2 v172, v[188:189], s[76:77]
	v_cvt_pk_fp8_f32 v8, v99, v103
	v_cvt_pk_fp8_f32 v9, v107, v111
	v_cvt_pk_fp8_f32 v10, v115, v119
	v_cvt_pk_fp8_f32 v11, v123, v127
	v_and_b32_e32 v8, 0xffff, v8
	v_and_b32_e32 v10, 0xffff, v10
	v_lshl_or_b32 v190, v9, 16, v8
	v_lshl_or_b32 v191, v11, 16, v10
	global_store_dwordx2 v173, v[190:191], s[76:77]
	s_waitcnt vmcnt(16)
	v_pk_mul_f32 v[128:129], v[128:129], s[44:45]
	v_pk_mul_f32 v[130:131], v[130:131], s[44:45]
	v_pk_mul_f32 v[132:133], v[132:133], s[44:45]
	v_pk_mul_f32 v[134:135], v[134:135], s[44:45]
	v_pk_mul_f32 v[136:137], v[136:137], s[44:45]
	v_pk_mul_f32 v[138:139], v[138:139], s[44:45]
	v_pk_mul_f32 v[140:141], v[140:141], s[44:45]
	v_pk_mul_f32 v[142:143], v[142:143], s[44:45]
	v_pk_mul_f32 v[144:145], v[144:145], s[44:45]
	v_pk_mul_f32 v[146:147], v[146:147], s[44:45]
	v_pk_mul_f32 v[148:149], v[148:149], s[44:45]
	v_pk_mul_f32 v[150:151], v[150:151], s[44:45]
	v_pk_mul_f32 v[152:153], v[152:153], s[44:45]
	v_pk_mul_f32 v[154:155], v[154:155], s[44:45]
	v_pk_mul_f32 v[156:157], v[156:157], s[44:45]
	v_pk_mul_f32 v[158:159], v[158:159], s[44:45]
	v_cvt_pk_fp8_f32 v8, v128, v132
	v_cvt_pk_fp8_f32 v9, v136, v140
	v_cvt_pk_fp8_f32 v10, v144, v148
	v_cvt_pk_fp8_f32 v11, v152, v156
	v_and_b32_e32 v8, 0xffff, v8
	v_and_b32_e32 v10, 0xffff, v10
	v_lshl_or_b32 v176, v9, 16, v8
	v_lshl_or_b32 v177, v11, 16, v10
	global_store_dwordx2 v170, v[176:177], s[78:79]
	v_cvt_pk_fp8_f32 v8, v129, v133
	v_cvt_pk_fp8_f32 v9, v137, v141
	v_cvt_pk_fp8_f32 v10, v145, v149
	v_cvt_pk_fp8_f32 v11, v153, v157
	v_and_b32_e32 v8, 0xffff, v8
	v_and_b32_e32 v10, 0xffff, v10
	v_lshl_or_b32 v178, v9, 16, v8
	v_lshl_or_b32 v179, v11, 16, v10
	global_store_dwordx2 v171, v[178:179], s[78:79]
	v_cvt_pk_fp8_f32 v8, v130, v134
	v_cvt_pk_fp8_f32 v9, v138, v142
	v_cvt_pk_fp8_f32 v10, v146, v150
	v_cvt_pk_fp8_f32 v11, v154, v158
	v_and_b32_e32 v8, 0xffff, v8
	v_and_b32_e32 v10, 0xffff, v10
	v_lshl_or_b32 v180, v9, 16, v8
	v_lshl_or_b32 v181, v11, 16, v10
	global_store_dwordx2 v172, v[180:181], s[78:79]
	v_cvt_pk_fp8_f32 v8, v131, v135
	v_cvt_pk_fp8_f32 v9, v139, v143
	v_cvt_pk_fp8_f32 v10, v147, v151
	v_cvt_pk_fp8_f32 v11, v155, v159
	v_and_b32_e32 v8, 0xffff, v8
	v_and_b32_e32 v10, 0xffff, v10
	v_lshl_or_b32 v182, v9, 16, v8
	v_lshl_or_b32 v183, v11, 16, v10
	global_store_dwordx2 v173, v[182:183], s[78:79]
	s_waitcnt vmcnt(8)
	v_pk_mul_f32 v[64:65], v[64:65], s[44:45]
	v_pk_mul_f32 v[66:67], v[66:67], s[44:45]
	v_pk_mul_f32 v[68:69], v[68:69], s[44:45]
	v_pk_mul_f32 v[70:71], v[70:71], s[44:45]
	v_pk_mul_f32 v[72:73], v[72:73], s[44:45]
	v_pk_mul_f32 v[74:75], v[74:75], s[44:45]
	v_pk_mul_f32 v[76:77], v[76:77], s[44:45]
	v_pk_mul_f32 v[78:79], v[78:79], s[44:45]
	v_pk_mul_f32 v[80:81], v[80:81], s[44:45]
	v_pk_mul_f32 v[82:83], v[82:83], s[44:45]
	v_pk_mul_f32 v[84:85], v[84:85], s[44:45]
	v_pk_mul_f32 v[86:87], v[86:87], s[44:45]
	v_pk_mul_f32 v[88:89], v[88:89], s[44:45]
	v_pk_mul_f32 v[90:91], v[90:91], s[44:45]
	v_pk_mul_f32 v[92:93], v[92:93], s[44:45]
	v_pk_mul_f32 v[94:95], v[94:95], s[44:45]
	v_cvt_pk_fp8_f32 v8, v64, v68
	v_cvt_pk_fp8_f32 v9, v72, v76
	v_cvt_pk_fp8_f32 v10, v80, v84
	v_cvt_pk_fp8_f32 v11, v88, v92
	v_and_b32_e32 v8, 0xffff, v8
	v_and_b32_e32 v10, 0xffff, v10
	v_lshl_or_b32 v184, v9, 16, v8
	v_lshl_or_b32 v185, v11, 16, v10
	global_store_dwordx2 v170, v[184:185], s[74:75]
	v_cvt_pk_fp8_f32 v8, v65, v69
	v_cvt_pk_fp8_f32 v9, v73, v77
	v_cvt_pk_fp8_f32 v10, v81, v85
	v_cvt_pk_fp8_f32 v11, v89, v93
	v_and_b32_e32 v8, 0xffff, v8
	v_and_b32_e32 v10, 0xffff, v10
	v_lshl_or_b32 v186, v9, 16, v8
	v_lshl_or_b32 v187, v11, 16, v10
	global_store_dwordx2 v171, v[186:187], s[74:75]
	v_cvt_pk_fp8_f32 v8, v66, v70
	v_cvt_pk_fp8_f32 v9, v74, v78
	v_cvt_pk_fp8_f32 v10, v82, v86
	v_cvt_pk_fp8_f32 v11, v90, v94
	v_and_b32_e32 v8, 0xffff, v8
	v_and_b32_e32 v10, 0xffff, v10
	v_lshl_or_b32 v188, v9, 16, v8
	v_lshl_or_b32 v189, v11, 16, v10
	global_store_dwordx2 v172, v[188:189], s[74:75]
	v_cvt_pk_fp8_f32 v8, v67, v71
	v_cvt_pk_fp8_f32 v9, v75, v79
	v_cvt_pk_fp8_f32 v10, v83, v87
	v_cvt_pk_fp8_f32 v11, v91, v95
	v_and_b32_e32 v8, 0xffff, v8
	v_and_b32_e32 v10, 0xffff, v10
	v_lshl_or_b32 v190, v9, 16, v8
	v_lshl_or_b32 v191, v11, 16, v10
	global_store_dwordx2 v173, v[190:191], s[74:75]
